# v54 with the hoisted rss loads issued before the epilogue-alignment barrier (in flight while the leading half waits)
# baseline (speedup 1.0000x reference)
; #define PG8_STAGE(bufoff, gbase, voff) do { _Pragma("unroll") for (int _i = 0; _i < 2; ++_i) \
;         __builtin_amdgcn_global_load_lds((const unsigned*)((const char*)(gbase) + (voff)[_i]), (PG8_LAS unsigned*)(lds + (bufoff) + ldsw + _i * 8192), 16, 0, 0); } while (0)
; #define PG8_LDA(dst, b, h) do { _Pragma("unroll") for (int m = 0; m < 4; ++m) _Pragma("unroll") for (int k = 0; k < 2; ++k) dst[m][k] = *(const PG8_LAS bf16x8*)(lds + PG8_SA(b, h) + aoff + m * 2048 + k * 1024); } while (0)
; #define PG8_LDB(dst, b, h) do { _Pragma("unroll") for (int n = 0; n < 2; ++n) _Pragma("unroll") for (int k = 0; k < 2; ++k) dst[n][k] = *(const PG8_LAS bf16x8*)(lds + PG8_SB(b, h) + boff + n * 2048 + k * 1024); } while (0)
; #define PG8_MMA(ai, bj, At, Bt) do { __builtin_amdgcn_s_setprio(1); _Pragma("unroll") for (int m = 0; m < 4; ++m) _Pragma("unroll") for (int n = 0; n < 2; ++n) _Pragma("unroll") for (int k = 0; k < 2; ++k) \
;         acc[ai][bj][m][n] = __builtin_amdgcn_mfma_f32_16x16x32_bf16(Bt[n][k], At[m][k], acc[ai][bj][m][n], 0, 0, 0); __builtin_amdgcn_s_setprio(0); } while (0)
; #define PG8_WAIT_V(n) asm volatile("s_waitcnt vmcnt(" #n ")" ::: "memory")
; #define PG8_WAIT_L(n) asm volatile("s_waitcnt lgkmcnt(" #n ")" ::: "memory")
; #define PG8_BAR __builtin_amdgcn_s_barrier()
; #define PG8_SCHED __builtin_amdgcn_sched_barrier(0)
; template <class Epi, class Sched, bool ALIGN_EPI = false, bool SP2 = false>
; __device__ __forceinline__ void gemm_phase(PG8_LAS unsigned char* lds, const Gemm g, const Sched& S, const Epi& E) {
;     ...
;             PG8_LDB(B0, 0, 0); PG8_LDB(B1, 0, 1); PG8_SCHED; PG8_LDA(At, 0, 0); PG8_STAGE(PG8_SA(1, 1), a1 + hstep, voffA);
;             PG8_WAIT_V(8); PG8_WAIT_L(0); PG8_BAR; PG8_MMA(0, 0, At, B0); PG8_MMA(0, 1, At, B1); PG8_BAR; PG8_SCHED;
;             PG8_LDA(At, 0, 1); PG8_STAGE(PG8_SB(0, 0), b2, voffB); PG8_STAGE(PG8_SB(0, 1), b2 + hstep, voffB); PG8_STAGE(PG8_SA(0, 0), a2, voffA);
;             PG8_WAIT_V(8); PG8_WAIT_L(0); PG8_BAR; PG8_MMA(1, 0, At, B0); PG8_MMA(1, 1, At, B1); PG8_BAR; PG8_SCHED;
.LBB0_131:
	ds_read_b128 v[140:143], v147
	ds_read_b128 v[152:155], v147 offset:1024
	ds_read_b128 v[156:159], v147 offset:2048
	ds_read_b128 v[164:167], v147 offset:3072
	ds_read_b128 v[168:171], v148
	ds_read_b128 v[172:175], v148 offset:1024
	ds_read_b128 v[176:179], v148 offset:2048
	ds_read_b128 v[180:183], v148 offset:3072
	s_add_u32 s26, s24, 0xfffc0080
	s_addc_u32 s27, s25, -1
	s_cmp_eq_u32 s54, 12
	s_cselect_b32 s29, s19, s27
	s_cselect_b32 s28, s50, s26
	s_cselect_b32 s27, s17, s53
	s_cselect_b32 s26, s51, s52
	v_lshl_add_u64 v[160:161], s[24:25], 0, v[134:135]
	s_add_i32 m0, s39, 0xc000
	ds_read_b128 v[184:187], v149
	ds_read_b128 v[188:191], v149 offset:1024
	ds_read_b128 v[192:195], v149 offset:2048
	ds_read_b128 v[196:199], v149 offset:3072
	ds_read_b128 v[200:203], v149 offset:4096
	ds_read_b128 v[204:207], v149 offset:5120
	ds_read_b128 v[208:211], v149 offset:6144
	ds_read_b128 v[212:215], v149 offset:7168
	global_load_lds_dwordx4 v[160:161], off
	v_lshl_add_u64 v[160:161], s[24:25], 0, v[136:137]
	s_add_i32 m0, s39, 0xe000
	s_nop 0
	global_load_lds_dwordx4 v[160:161], off
	s_waitcnt vmcnt(8)
	s_waitcnt lgkmcnt(0)
	s_barrier
	s_setprio 1
	s_waitcnt lgkmcnt(0)
	v_mfma_f32_16x16x32_bf16 v[122:125], v[140:143], v[184:187], v[122:125]
	v_mfma_f32_16x16x32_bf16 v[114:117], v[156:159], v[184:187], v[114:117]
	v_mfma_f32_16x16x32_bf16 v[106:109], v[140:143], v[192:195], v[106:109]
	v_mfma_f32_16x16x32_bf16 v[98:101], v[156:159], v[192:195], v[98:101]
	v_mfma_f32_16x16x32_bf16 v[90:93], v[140:143], v[200:203], v[90:93]
	v_mfma_f32_16x16x32_bf16 v[82:85], v[156:159], v[200:203], v[82:85]
	v_mfma_f32_16x16x32_bf16 v[74:77], v[140:143], v[208:211], v[74:77]
	v_mfma_f32_16x16x32_bf16 v[70:73], v[156:159], v[208:211], v[70:73]
	v_mfma_f32_16x16x32_bf16 v[122:125], v[152:155], v[188:191], v[122:125]
	v_mfma_f32_16x16x32_bf16 v[114:117], v[164:167], v[188:191], v[114:117]
	v_mfma_f32_16x16x32_bf16 v[106:109], v[152:155], v[196:199], v[106:109]
	v_mfma_f32_16x16x32_bf16 v[98:101], v[164:167], v[196:199], v[98:101]
	v_mfma_f32_16x16x32_bf16 v[90:93], v[152:155], v[204:207], v[90:93]
	v_mfma_f32_16x16x32_bf16 v[82:85], v[164:167], v[204:207], v[82:85]
	v_mfma_f32_16x16x32_bf16 v[74:77], v[152:155], v[212:215], v[74:77]
	v_mfma_f32_16x16x32_bf16 v[70:73], v[164:167], v[212:215], v[70:73]
	s_setprio 0
	s_setprio 1
	v_mfma_f32_16x16x32_bf16 v[126:129], v[168:171], v[184:187], v[126:129]
	v_mfma_f32_16x16x32_bf16 v[118:121], v[176:179], v[184:187], v[118:121]
	v_mfma_f32_16x16x32_bf16 v[110:113], v[168:171], v[192:195], v[110:113]
	v_mfma_f32_16x16x32_bf16 v[102:105], v[176:179], v[192:195], v[102:105]
	v_mfma_f32_16x16x32_bf16 v[94:97], v[168:171], v[200:203], v[94:97]
	v_mfma_f32_16x16x32_bf16 v[86:89], v[176:179], v[200:203], v[86:89]
	v_mfma_f32_16x16x32_bf16 v[78:81], v[168:171], v[208:211], v[78:81]
	v_mfma_f32_16x16x32_bf16 v[66:69], v[176:179], v[208:211], v[66:69]
	v_mfma_f32_16x16x32_bf16 v[126:129], v[172:175], v[188:191], v[126:129]
	v_mfma_f32_16x16x32_bf16 v[118:121], v[180:183], v[188:191], v[118:121]
	v_mfma_f32_16x16x32_bf16 v[110:113], v[172:175], v[196:199], v[110:113]
	v_mfma_f32_16x16x32_bf16 v[102:105], v[180:183], v[196:199], v[102:105]
	v_mfma_f32_16x16x32_bf16 v[94:97], v[172:175], v[204:207], v[94:97]
	v_mfma_f32_16x16x32_bf16 v[86:89], v[180:183], v[204:207], v[86:89]
	v_mfma_f32_16x16x32_bf16 v[78:81], v[172:175], v[212:215], v[78:81]
	v_mfma_f32_16x16x32_bf16 v[66:69], v[180:183], v[212:215], v[66:69]
	s_setprio 0
	s_barrier
	s_add_i32 s55, s8, s37
	v_lshl_add_u64 v[160:161], s[26:27], 0, v[132:133]
	s_mov_b32 m0, s55
	ds_read_b128 v[184:187], v149 offset:16384
	ds_read_b128 v[188:191], v149 offset:17408
	ds_read_b128 v[192:195], v149 offset:18432
	ds_read_b128 v[196:199], v149 offset:19456
	ds_read_b128 v[200:203], v149 offset:20480
	ds_read_b128 v[204:207], v149 offset:21504
	ds_read_b128 v[208:211], v149 offset:22528
	ds_read_b128 v[212:215], v149 offset:23552
	global_load_lds_dwordx4 v[160:161], off
	s_add_i32 m0, s55, 0x2000
	s_add_u32 s56, s26, 0x40000
	v_lshl_add_u64 v[216:217], s[26:27], 0, v[130:131]
	s_addc_u32 s57, s27, 0
	s_add_i32 s55, s46, s37
	global_load_lds_dwordx4 v[216:217], off
	v_lshl_add_u64 v[218:219], s[56:57], 0, v[132:133]
	s_mov_b32 m0, s55
	v_lshl_add_u64 v[220:221], s[28:29], 0, v[130:131]
	global_load_lds_dwordx4 v[218:219], off
	v_lshl_add_u64 v[218:219], s[56:57], 0, v[130:131]
	s_add_i32 m0, s55, 0x2000
	s_nop 0
	global_load_lds_dwordx4 v[218:219], off
	v_lshl_add_u64 v[218:219], s[28:29], 0, v[132:133]
	s_mov_b32 m0, s39
	s_nop 0
	global_load_lds_dwordx4 v[218:219], off
	s_mov_b32 m0, s40
	s_nop 0
	global_load_lds_dwordx4 v[220:221], off
	s_waitcnt vmcnt(8)
	s_waitcnt lgkmcnt(0)
	s_barrier
; #define PG8_STAGE(bufoff, gbase, voff) do { _Pragma("unroll") for (int _i = 0; _i < 2; ++_i) \
;         __builtin_amdgcn_global_load_lds((const unsigned*)((const char*)(gbase) + (voff)[_i]), (PG8_LAS unsigned*)(lds + (bufoff) + ldsw + _i * 8192), 16, 0, 0); } while (0)
; #define PG8_LDA(dst, b, h) do { _Pragma("unroll") for (int m = 0; m < 4; ++m) _Pragma("unroll") for (int k = 0; k < 2; ++k) dst[m][k] = *(const PG8_LAS bf16x8*)(lds + PG8_SA(b, h) + aoff + m * 2048 + k * 1024); } while (0)
; #define PG8_LDB(dst, b, h) do { _Pragma("unroll") for (int n = 0; n < 2; ++n) _Pragma("unroll") for (int k = 0; k < 2; ++k) dst[n][k] = *(const PG8_LAS bf16x8*)(lds + PG8_SB(b, h) + boff + n * 2048 + k * 1024); } while (0)
; #define PG8_MMA(ai, bj, At, Bt) do { __builtin_amdgcn_s_setprio(1); _Pragma("unroll") for (int m = 0; m < 4; ++m) _Pragma("unroll") for (int n = 0; n < 2; ++n) _Pragma("unroll") for (int k = 0; k < 2; ++k) \
;         acc[ai][bj][m][n] = __builtin_amdgcn_mfma_f32_16x16x32_bf16(Bt[n][k], At[m][k], acc[ai][bj][m][n], 0, 0, 0); __builtin_amdgcn_s_setprio(0); } while (0)
; #define PG8_WAIT_V(n) asm volatile("s_waitcnt vmcnt(" #n ")" ::: "memory")
; #define PG8_WAIT_L(n) asm volatile("s_waitcnt lgkmcnt(" #n ")" ::: "memory")
; #define PG8_BAR __builtin_amdgcn_s_barrier()
; #define PG8_SCHED __builtin_amdgcn_sched_barrier(0)
; template <class Epi, class Sched, bool ALIGN_EPI = false, bool SP2 = false>
; __device__ __forceinline__ void gemm_phase(PG8_LAS unsigned char* lds, const Gemm g, const Sched& S, const Epi& E) {
;     ...
;             PG8_WAIT_V(8); PG8_WAIT_L(0); PG8_BAR; PG8_MMA(1, 0, At, B0); PG8_MMA(1, 1, At, B1); PG8_BAR; PG8_SCHED;
;             PG8_LDB(B0, 1, 0); PG8_LDB(B1, 1, 1); PG8_SCHED; PG8_LDA(At, 1, 0); PG8_STAGE(PG8_SA(0, 1), a2 + hstep, voffA);
;             PG8_WAIT_V(8); PG8_WAIT_L(0); PG8_BAR; PG8_MMA(0, 0, At, B0); PG8_MMA(0, 1, At, B1); PG8_BAR; PG8_SCHED;
	s_setprio 1
	s_waitcnt lgkmcnt(0)
	v_mfma_f32_16x16x32_bf16 v[58:61], v[140:143], v[184:187], v[58:61]
	v_mfma_f32_16x16x32_bf16 v[54:57], v[156:159], v[184:187], v[54:57]
	v_mfma_f32_16x16x32_bf16 v[42:45], v[140:143], v[192:195], v[42:45]
	v_mfma_f32_16x16x32_bf16 v[38:41], v[156:159], v[192:195], v[38:41]
	v_mfma_f32_16x16x32_bf16 v[26:29], v[140:143], v[200:203], v[26:29]
	v_mfma_f32_16x16x32_bf16 v[22:25], v[156:159], v[200:203], v[22:25]
	v_mfma_f32_16x16x32_bf16 v[10:13], v[140:143], v[208:211], v[10:13]
	v_mfma_f32_16x16x32_bf16 v[6:9], v[156:159], v[208:211], v[6:9]
	v_mfma_f32_16x16x32_bf16 v[58:61], v[152:155], v[188:191], v[58:61]
	v_mfma_f32_16x16x32_bf16 v[54:57], v[164:167], v[188:191], v[54:57]
	v_mfma_f32_16x16x32_bf16 v[42:45], v[152:155], v[196:199], v[42:45]
	v_mfma_f32_16x16x32_bf16 v[38:41], v[164:167], v[196:199], v[38:41]
	v_mfma_f32_16x16x32_bf16 v[26:29], v[152:155], v[204:207], v[26:29]
	v_mfma_f32_16x16x32_bf16 v[22:25], v[164:167], v[204:207], v[22:25]
	v_mfma_f32_16x16x32_bf16 v[10:13], v[152:155], v[212:215], v[10:13]
	v_mfma_f32_16x16x32_bf16 v[6:9], v[164:167], v[212:215], v[6:9]
	s_setprio 0
	s_setprio 1
	v_mfma_f32_16x16x32_bf16 v[62:65], v[168:171], v[184:187], v[62:65]
	v_mfma_f32_16x16x32_bf16 v[50:53], v[176:179], v[184:187], v[50:53]
	v_mfma_f32_16x16x32_bf16 v[46:49], v[168:171], v[192:195], v[46:49]
	v_mfma_f32_16x16x32_bf16 v[34:37], v[176:179], v[192:195], v[34:37]
	v_mfma_f32_16x16x32_bf16 v[30:33], v[168:171], v[200:203], v[30:33]
	v_mfma_f32_16x16x32_bf16 v[18:21], v[176:179], v[200:203], v[18:21]
	v_mfma_f32_16x16x32_bf16 v[14:17], v[168:171], v[208:211], v[14:17]
	v_mfma_f32_16x16x32_bf16 v[2:5], v[176:179], v[208:211], v[2:5]
	v_mfma_f32_16x16x32_bf16 v[62:65], v[172:175], v[188:191], v[62:65]
	v_mfma_f32_16x16x32_bf16 v[50:53], v[180:183], v[188:191], v[50:53]
	v_mfma_f32_16x16x32_bf16 v[46:49], v[172:175], v[196:199], v[46:49]
	v_mfma_f32_16x16x32_bf16 v[34:37], v[180:183], v[196:199], v[34:37]
	v_mfma_f32_16x16x32_bf16 v[30:33], v[172:175], v[204:207], v[30:33]
	v_mfma_f32_16x16x32_bf16 v[18:21], v[180:183], v[204:207], v[18:21]
	v_mfma_f32_16x16x32_bf16 v[14:17], v[172:175], v[212:215], v[14:17]
	v_mfma_f32_16x16x32_bf16 v[2:5], v[180:183], v[212:215], v[2:5]
	s_setprio 0
	s_barrier
	s_add_i32 s55, 0, 0x18000
	v_add_u32_e32 v151, s55, v145
	s_add_i32 s56, 0, 0x1c000
	ds_read_b128 v[140:143], v151
	ds_read_b128 v[152:155], v151 offset:1024
	ds_read_b128 v[156:159], v151 offset:2048
	ds_read_b128 v[164:167], v151 offset:3072
	v_add_u32_e32 v151, s56, v145
	ds_read_b128 v[168:171], v151
	ds_read_b128 v[172:175], v151 offset:1024
	ds_read_b128 v[176:179], v151 offset:2048
	ds_read_b128 v[180:183], v151 offset:3072
	s_add_u32 s28, s28, 0x40000
	s_addc_u32 s29, s29, 0
	s_mov_b32 m0, s41
	v_lshl_add_u64 v[222:223], s[28:29], 0, v[132:133]
	ds_read_b128 v[184:187], v149 offset:32768
	ds_read_b128 v[188:191], v149 offset:33792
	ds_read_b128 v[192:195], v149 offset:34816
	ds_read_b128 v[196:199], v149 offset:35840
	ds_read_b128 v[200:203], v149 offset:36864
	ds_read_b128 v[204:207], v149 offset:37888
	ds_read_b128 v[208:211], v149 offset:38912
	ds_read_b128 v[212:215], v149 offset:39936
	global_load_lds_dwordx4 v[222:223], off
	v_lshl_add_u64 v[222:223], s[28:29], 0, v[130:131]
	s_mov_b32 m0, s42
	s_nop 0
	global_load_lds_dwordx4 v[222:223], off
	s_waitcnt vmcnt(8)
	s_waitcnt lgkmcnt(0)
	s_barrier
	s_setprio 1
	s_waitcnt lgkmcnt(0)
	v_mfma_f32_16x16x32_bf16 v[122:125], v[140:143], v[184:187], v[122:125]
	v_mfma_f32_16x16x32_bf16 v[114:117], v[156:159], v[184:187], v[114:117]
	v_mfma_f32_16x16x32_bf16 v[106:109], v[140:143], v[192:195], v[106:109]
	v_mfma_f32_16x16x32_bf16 v[98:101], v[156:159], v[192:195], v[98:101]
	v_mfma_f32_16x16x32_bf16 v[90:93], v[140:143], v[200:203], v[90:93]
	v_mfma_f32_16x16x32_bf16 v[82:85], v[156:159], v[200:203], v[82:85]
	v_mfma_f32_16x16x32_bf16 v[74:77], v[140:143], v[208:211], v[74:77]
	v_mfma_f32_16x16x32_bf16 v[70:73], v[156:159], v[208:211], v[70:73]
	v_mfma_f32_16x16x32_bf16 v[122:125], v[152:155], v[188:191], v[122:125]
	v_mfma_f32_16x16x32_bf16 v[114:117], v[164:167], v[188:191], v[114:117]
	v_mfma_f32_16x16x32_bf16 v[106:109], v[152:155], v[196:199], v[106:109]
	v_mfma_f32_16x16x32_bf16 v[98:101], v[164:167], v[196:199], v[98:101]
	v_mfma_f32_16x16x32_bf16 v[90:93], v[152:155], v[204:207], v[90:93]
	v_mfma_f32_16x16x32_bf16 v[82:85], v[164:167], v[204:207], v[82:85]
	v_mfma_f32_16x16x32_bf16 v[74:77], v[152:155], v[212:215], v[74:77]
	v_mfma_f32_16x16x32_bf16 v[70:73], v[164:167], v[212:215], v[70:73]
	s_setprio 0
	s_setprio 1
	v_mfma_f32_16x16x32_bf16 v[126:129], v[168:171], v[184:187], v[126:129]
	v_mfma_f32_16x16x32_bf16 v[118:121], v[176:179], v[184:187], v[118:121]
	v_mfma_f32_16x16x32_bf16 v[110:113], v[168:171], v[192:195], v[110:113]
	v_mfma_f32_16x16x32_bf16 v[102:105], v[176:179], v[192:195], v[102:105]
	v_mfma_f32_16x16x32_bf16 v[94:97], v[168:171], v[200:203], v[94:97]
	v_mfma_f32_16x16x32_bf16 v[86:89], v[176:179], v[200:203], v[86:89]
	v_mfma_f32_16x16x32_bf16 v[78:81], v[168:171], v[208:211], v[78:81]
	v_mfma_f32_16x16x32_bf16 v[66:69], v[176:179], v[208:211], v[66:69]
	v_mfma_f32_16x16x32_bf16 v[126:129], v[172:175], v[188:191], v[126:129]
	v_mfma_f32_16x16x32_bf16 v[118:121], v[180:183], v[188:191], v[118:121]
	v_mfma_f32_16x16x32_bf16 v[110:113], v[172:175], v[196:199], v[110:113]
	v_mfma_f32_16x16x32_bf16 v[102:105], v[180:183], v[196:199], v[102:105]
	v_mfma_f32_16x16x32_bf16 v[94:97], v[172:175], v[204:207], v[94:97]
	v_mfma_f32_16x16x32_bf16 v[86:89], v[180:183], v[204:207], v[86:89]
	v_mfma_f32_16x16x32_bf16 v[78:81], v[172:175], v[212:215], v[78:81]
	v_mfma_f32_16x16x32_bf16 v[66:69], v[180:183], v[212:215], v[66:69]
	s_setprio 0
	s_barrier
; #define PG8_STAGE(bufoff, gbase, voff) do { _Pragma("unroll") for (int _i = 0; _i < 2; ++_i) \
;         __builtin_amdgcn_global_load_lds((const unsigned*)((const char*)(gbase) + (voff)[_i]), (PG8_LAS unsigned*)(lds + (bufoff) + ldsw + _i * 8192), 16, 0, 0); } while (0)
; #define PG8_LDA(dst, b, h) do { _Pragma("unroll") for (int m = 0; m < 4; ++m) _Pragma("unroll") for (int k = 0; k < 2; ++k) dst[m][k] = *(const PG8_LAS bf16x8*)(lds + PG8_SA(b, h) + aoff + m * 2048 + k * 1024); } while (0)
; #define PG8_MMA(ai, bj, At, Bt) do { __builtin_amdgcn_s_setprio(1); _Pragma("unroll") for (int m = 0; m < 4; ++m) _Pragma("unroll") for (int n = 0; n < 2; ++n) _Pragma("unroll") for (int k = 0; k < 2; ++k) \
;         acc[ai][bj][m][n] = __builtin_amdgcn_mfma_f32_16x16x32_bf16(Bt[n][k], At[m][k], acc[ai][bj][m][n], 0, 0, 0); __builtin_amdgcn_s_setprio(0); } while (0)
; #define PG8_WAIT_V(n) asm volatile("s_waitcnt vmcnt(" #n ")" ::: "memory")
; #define PG8_WAIT_L(n) asm volatile("s_waitcnt lgkmcnt(" #n ")" ::: "memory")
; #define PG8_BAR __builtin_amdgcn_s_barrier()
; #define PG8_SCHED __builtin_amdgcn_sched_barrier(0)
; template <class Epi, class Sched, bool ALIGN_EPI = false, bool SP2 = false>
; __device__ __forceinline__ void gemm_phase(PG8_LAS unsigned char* lds, const Gemm g, const Sched& S, const Epi& E) {
;     ...
;             PG8_LDA(At, 1, 1); PG8_STAGE(PG8_SB(1, 0), b3, voffB); PG8_STAGE(PG8_SB(1, 1), b3 + hstep, voffB); PG8_STAGE(PG8_SA(1, 0), a3, voffA);
;             PG8_WAIT_V(8); PG8_WAIT_L(0); PG8_BAR; PG8_MMA(1, 0, At, B0); PG8_MMA(1, 1, At, B1); PG8_BAR; PG8_SCHED;
;     ...
;         if constexpr (ALIGN_EPI) { if (wr == 0) PG8_BAR; }
;         if constexpr (!Epi::AFTER_DRAIN) { E(acc, cur, wr, wc, fr, fq); S.done(cur); }
	s_add_i32 s28, s55, s37
	v_lshl_add_u64 v[160:161], v[160:161], 0, s[12:13]
	s_mov_b32 m0, s28
	ds_read_b128 v[184:187], v149 offset:49152
	ds_read_b128 v[188:191], v149 offset:50176
	ds_read_b128 v[192:195], v149 offset:51200
	ds_read_b128 v[196:199], v149 offset:52224
	ds_read_b128 v[200:203], v149 offset:53248
	ds_read_b128 v[204:207], v149 offset:54272
	ds_read_b128 v[208:211], v149 offset:55296
	ds_read_b128 v[212:215], v149 offset:56320
	global_load_lds_dwordx4 v[160:161], off
	s_add_i32 m0, s28, 0x2000
	s_add_u32 s26, s26, 0x40080
	v_lshl_add_u64 v[160:161], v[216:217], 0, s[12:13]
	s_addc_u32 s27, s27, 0
	s_add_i32 s28, s56, s37
	global_load_lds_dwordx4 v[160:161], off
	v_lshl_add_u64 v[160:161], s[26:27], 0, v[132:133]
	s_mov_b32 m0, s28
	s_nop 0
	global_load_lds_dwordx4 v[160:161], off
	v_lshl_add_u64 v[160:161], s[26:27], 0, v[130:131]
	s_add_i32 m0, s28, 0x2000
	s_nop 0
	global_load_lds_dwordx4 v[160:161], off
	v_lshl_add_u64 v[160:161], v[218:219], 0, s[12:13]
	s_mov_b32 m0, s43
	s_nop 0
	global_load_lds_dwordx4 v[160:161], off
	v_lshl_add_u64 v[160:161], v[220:221], 0, s[12:13]
	s_mov_b32 m0, s44
	s_nop 0
	global_load_lds_dwordx4 v[160:161], off
	s_waitcnt vmcnt(8)
	s_waitcnt lgkmcnt(0)
	s_barrier
	s_setprio 1
	s_waitcnt lgkmcnt(0)
	v_mfma_f32_16x16x32_bf16 v[58:61], v[140:143], v[184:187], v[58:61]
	v_mfma_f32_16x16x32_bf16 v[54:57], v[156:159], v[184:187], v[54:57]
	v_mfma_f32_16x16x32_bf16 v[42:45], v[140:143], v[192:195], v[42:45]
	v_mfma_f32_16x16x32_bf16 v[38:41], v[156:159], v[192:195], v[38:41]
	v_mfma_f32_16x16x32_bf16 v[26:29], v[140:143], v[200:203], v[26:29]
	v_mfma_f32_16x16x32_bf16 v[22:25], v[156:159], v[200:203], v[22:25]
	v_mfma_f32_16x16x32_bf16 v[10:13], v[140:143], v[208:211], v[10:13]
	v_mfma_f32_16x16x32_bf16 v[6:9], v[156:159], v[208:211], v[6:9]
	v_mfma_f32_16x16x32_bf16 v[58:61], v[152:155], v[188:191], v[58:61]
	v_mfma_f32_16x16x32_bf16 v[54:57], v[164:167], v[188:191], v[54:57]
	v_mfma_f32_16x16x32_bf16 v[42:45], v[152:155], v[196:199], v[42:45]
	v_mfma_f32_16x16x32_bf16 v[38:41], v[164:167], v[196:199], v[38:41]
	v_mfma_f32_16x16x32_bf16 v[26:29], v[152:155], v[204:207], v[26:29]
	v_mfma_f32_16x16x32_bf16 v[22:25], v[164:167], v[204:207], v[22:25]
	v_mfma_f32_16x16x32_bf16 v[10:13], v[152:155], v[212:215], v[10:13]
	v_mfma_f32_16x16x32_bf16 v[6:9], v[164:167], v[212:215], v[6:9]
	s_setprio 0
	s_setprio 1
	v_mfma_f32_16x16x32_bf16 v[62:65], v[168:171], v[184:187], v[62:65]
	v_mfma_f32_16x16x32_bf16 v[50:53], v[176:179], v[184:187], v[50:53]
	v_mfma_f32_16x16x32_bf16 v[46:49], v[168:171], v[192:195], v[46:49]
	v_mfma_f32_16x16x32_bf16 v[34:37], v[176:179], v[192:195], v[34:37]
	v_mfma_f32_16x16x32_bf16 v[30:33], v[168:171], v[200:203], v[30:33]
	v_mfma_f32_16x16x32_bf16 v[18:21], v[176:179], v[200:203], v[18:21]
	v_mfma_f32_16x16x32_bf16 v[14:17], v[168:171], v[208:211], v[14:17]
	v_mfma_f32_16x16x32_bf16 v[2:5], v[176:179], v[208:211], v[2:5]
	v_mfma_f32_16x16x32_bf16 v[62:65], v[172:175], v[188:191], v[62:65]
	v_mfma_f32_16x16x32_bf16 v[50:53], v[180:183], v[188:191], v[50:53]
	v_mfma_f32_16x16x32_bf16 v[46:49], v[172:175], v[196:199], v[46:49]
	v_mfma_f32_16x16x32_bf16 v[34:37], v[180:183], v[196:199], v[34:37]
	v_mfma_f32_16x16x32_bf16 v[30:33], v[172:175], v[204:207], v[30:33]
	v_mfma_f32_16x16x32_bf16 v[18:21], v[180:183], v[204:207], v[18:21]
	v_mfma_f32_16x16x32_bf16 v[14:17], v[172:175], v[212:215], v[14:17]
	v_mfma_f32_16x16x32_bf16 v[2:5], v[180:183], v[212:215], v[2:5]
	s_setprio 0
	s_barrier
	s_add_i32 s54, s54, 2
	s_add_u32 s24, s24, 0x100
	s_addc_u32 s25, s25, 0
	s_add_u32 s52, s52, 0x100
	s_addc_u32 s53, s53, 0
	s_cmp_gt_u32 s54, 13
	s_cbranch_scc0 .LBB0_131
	v_lshl_add_u32 v140, s48, 8, v144
	v_ashrrev_i32_e32 v141, 31, v140
	v_lshl_add_u64 v[142:143], v[140:141], 2, s[4:5]
	global_load_dword v200, v[142:143], off
	global_load_dword v201, v[142:143], off offset:64
	global_load_dword v202, v[142:143], off offset:128
	global_load_dword v203, v[142:143], off offset:192
	global_load_dword v204, v[142:143], off offset:512
	global_load_dword v205, v[142:143], off offset:576
	global_load_dword v206, v[142:143], off offset:640
	global_load_dword v207, v[142:143], off offset:704
	s_and_b64 vcc, exec, s[14:15]
	s_cbranch_vccz .LBB0_134
	s_barrier
; __device__ __forceinline__ unsigned cvt_pk_bf16(float lo, float hi) { unsigned r; asm volatile("v_cvt_pk_bf16_f32 %0, %1, %2" : "=v"(r) : "v"(lo), "v"(hi)); return r; }
; __device__ __forceinline__ float silu_f(float x) { return x * sigmoid_f(x); }
;     __device__ __forceinline__ void operator()(const f32x4 (&acc)[2][2][4][2], const Unit& u, int wr, int wc, int fr, int fq) const {
;     ...
;             for (int m = 0; m < 4; ++m) {
;                 const int row = row0 + ai * HALF + m * 16;
;                 const float r = __builtin_amdgcn_rsqf(rss[row] * (1.f / 1024.f) + NEPS);
;                 float o[8];
; #pragma unroll
;                 for (int n = 0; n < 2; ++n)
; #pragma unroll
;                     for (int e = 0; e < 4; ++e) o[4 * n + e] = silu_f(acc[ai][0][m][n][e] * r) * (acc[ai][1][m][n][e] * r);
;                 u32x4 w; w.x = cvt_pk_bf16(o[0], o[1]); w.y = cvt_pk_bf16(o[2], o[3]); w.z = cvt_pk_bf16(o[4], o[5]); w.w = cvt_pk_bf16(o[6], o[7]);
;                 *(u32x4*)(O + (size_t)row * 2816 + col0) = w;
.LBB0_134:
	v_lshl_or_b32 v152, s49, 7, v146
	v_ashrrev_i32_e32 v153, 31, v152
	v_mov_b32_e32 v156, v120
	v_mov_b32_e32 v157, v116
	v_mov_b32_e32 v116, v121
	v_lshlrev_b64 v[120:121], 1, v[152:153]
	v_mov_b32_e32 v154, v126
	v_mov_b32_e32 v155, v122
	v_mov_b32_e32 v122, v127
	v_mov_b32_e32 v126, v128
	v_mov_b32_e32 v127, v124
	v_mov_b32_e32 v124, v129
	v_mov_b32_e32 v128, v118
	v_mov_b32_e32 v129, v114
	v_mov_b32_e32 v114, v119
	v_or_b32_e32 v160, 16, v140
	v_ashrrev_i32_e32 v161, 31, v160
	v_lshl_add_u64 v[164:165], v[160:161], 2, s[4:5]
	v_mov_b64_e32 v[118:119], s[60:61]
	v_mad_i64_i32 v[158:159], s[24:25], v140, s47, v[118:119]
	v_lshl_add_u64 v[158:159], v[158:159], 0, v[120:121]
	s_andn2_b64 vcc, exec, s[6:7]
	s_mov_b64 s[6:7], -1
	s_waitcnt vmcnt(0)
	v_mov_b32_e32 v141, v200
	v_fmamk_f32 v141, v141, 0x3a800000, v150
	v_rsq_f32_e32 v152, v141
	s_nop 0
	v_pk_mul_f32 v[116:117], v[116:117], v[152:153] op_sel_hi:[1,0]
	v_pk_mul_f32 v[154:155], v[154:155], v[152:153] op_sel_hi:[1,0]
	v_pk_mul_f32 v[122:123], v[122:123], v[152:153] op_sel_hi:[1,0]
	v_pk_mul_f32 v[126:127], v[126:127], v[152:153] op_sel_hi:[1,0]
	v_pk_mul_f32 v[124:125], v[124:125], v[152:153] op_sel_hi:[1,0]
	v_pk_mul_f32 v[128:129], v[128:129], v[152:153] op_sel_hi:[1,0]
	v_pk_mul_f32 v[114:115], v[114:115], v[152:153] op_sel_hi:[1,0]
	v_pk_mul_f32 v[156:157], v[156:157], v[152:153] op_sel_hi:[1,0]
	v_mul_f32_e32 v167, 0xbfb8aa3b, v117
	v_mul_f32_e32 v141, 0xbfb8aa3b, v155
	v_mul_f32_e32 v151, 0xbfb8aa3b, v123
	v_mul_f32_e32 v152, 0xbfb8aa3b, v127
	v_mul_f32_e32 v153, 0xbfb8aa3b, v125
	v_mul_f32_e32 v161, 0xbfb8aa3b, v129
	v_mul_f32_e32 v163, 0xbfb8aa3b, v115
	v_mul_f32_e32 v166, 0xbfb8aa3b, v157
	v_exp_f32_e32 v167, v167
	v_exp_f32_e32 v141, v141
	v_exp_f32_e32 v151, v151
	v_exp_f32_e32 v152, v152
	v_exp_f32_e32 v153, v153
	v_exp_f32_e32 v161, v161
	v_exp_f32_e32 v163, v163
	v_exp_f32_e32 v166, v166
	v_add_f32_e32 v167, 1.0, v167
	v_add_f32_e32 v141, 1.0, v141
	v_add_f32_e32 v151, 1.0, v151
	v_add_f32_e32 v152, 1.0, v152
	v_add_f32_e32 v153, 1.0, v153
	v_add_f32_e32 v161, 1.0, v161
	v_add_f32_e32 v163, 1.0, v163
	v_add_f32_e32 v166, 1.0, v166
	v_rcp_f32_e32 v167, v167
	v_rcp_f32_e32 v141, v141
	v_rcp_f32_e32 v151, v151
	v_rcp_f32_e32 v152, v152
	v_rcp_f32_e32 v153, v153
	v_rcp_f32_e32 v161, v161
	v_rcp_f32_e32 v163, v163
	v_rcp_f32_e32 v166, v166
	v_mul_f32_e32 v117, v117, v167
	v_mul_f32_e32 v141, v155, v141
	v_mul_f32_e32 v123, v123, v151
	v_mul_f32_e32 v127, v127, v152
	v_mul_f32_e32 v125, v125, v153
	v_mul_f32_e32 v129, v129, v161
	v_mul_f32_e32 v115, v115, v163
	v_mul_f32_e32 v151, v157, v166
	v_mul_f32_e32 v117, v116, v117
	v_mul_f32_e32 v141, v154, v141
	v_mul_f32_e32 v122, v122, v123
	v_mul_f32_e32 v123, v126, v127
	v_mul_f32_e32 v124, v124, v125
	v_mul_f32_e32 v125, v128, v129
	v_mul_f32_e32 v126, v114, v115
	v_mul_f32_e32 v127, v156, v151
	v_cvt_pk_bf16_f32 v114, v141, v122
	v_cvt_pk_bf16_f32 v115, v123, v124
	v_cvt_pk_bf16_f32 v116, v125, v126
	v_cvt_pk_bf16_f32 v117, v127, v117
	global_store_dwordx4 v[158:159], v[114:117], off
	s_nop 0
	s_nop 0
	v_mov_b32_e32 v115, v106
	v_mov_b32_e32 v106, v111
	v_mov_b32_e32 v111, v108
	v_mov_b32_e32 v108, v113
	v_mov_b32_e32 v113, v98
	v_mov_b32_e32 v98, v103
	v_mov_b32_e32 v103, v100
	v_mov_b32_e32 v100, v105
	v_mov_b32_e32 v114, v110
	v_mov_b32_e32 v110, v112
	v_mov_b32_e32 v112, v102
	v_mov_b32_e32 v102, v104
	v_or_b32_e32 v104, 32, v140
	v_mad_i64_i32 v[116:117], s[24:25], v160, s47, v[118:119]
	v_lshl_add_u64 v[116:117], v[116:117], 0, v[120:121]
	s_waitcnt vmcnt(7)
	v_mov_b32_e32 v122, v201
	v_fmamk_f32 v105, v122, 0x3a800000, v150
	v_rsq_f32_e32 v122, v105
	v_ashrrev_i32_e32 v105, 31, v104
	v_lshl_add_u64 v[124:125], v[104:105], 2, s[4:5]
	v_pk_mul_f32 v[100:101], v[100:101], v[122:123] op_sel_hi:[1,0]
	v_pk_mul_f32 v[114:115], v[114:115], v[122:123] op_sel_hi:[1,0]
	v_pk_mul_f32 v[106:107], v[106:107], v[122:123] op_sel_hi:[1,0]
	v_pk_mul_f32 v[110:111], v[110:111], v[122:123] op_sel_hi:[1,0]
	v_pk_mul_f32 v[108:109], v[108:109], v[122:123] op_sel_hi:[1,0]
	v_pk_mul_f32 v[112:113], v[112:113], v[122:123] op_sel_hi:[1,0]
	v_pk_mul_f32 v[98:99], v[98:99], v[122:123] op_sel_hi:[1,0]
	v_pk_mul_f32 v[102:103], v[102:103], v[122:123] op_sel_hi:[1,0]
	v_mul_f32_e32 v141, 0xbfb8aa3b, v101
	v_mul_f32_e32 v105, 0xbfb8aa3b, v115
	v_mul_f32_e32 v122, 0xbfb8aa3b, v107
	v_mul_f32_e32 v123, 0xbfb8aa3b, v111
	v_mul_f32_e32 v126, 0xbfb8aa3b, v109
	v_mul_f32_e32 v127, 0xbfb8aa3b, v113
	v_mul_f32_e32 v128, 0xbfb8aa3b, v99
	v_mul_f32_e32 v129, 0xbfb8aa3b, v103
	v_exp_f32_e32 v141, v141
	v_exp_f32_e32 v105, v105
	v_exp_f32_e32 v122, v122
	v_exp_f32_e32 v123, v123
	v_exp_f32_e32 v126, v126
	v_exp_f32_e32 v127, v127
	v_exp_f32_e32 v128, v128
	v_exp_f32_e32 v129, v129
	v_add_f32_e32 v141, 1.0, v141
	v_add_f32_e32 v105, 1.0, v105
	v_add_f32_e32 v122, 1.0, v122
	v_add_f32_e32 v123, 1.0, v123
	v_add_f32_e32 v126, 1.0, v126
	v_add_f32_e32 v127, 1.0, v127
	v_add_f32_e32 v128, 1.0, v128
	v_add_f32_e32 v129, 1.0, v129
	v_rcp_f32_e32 v141, v141
	v_rcp_f32_e32 v105, v105
	v_rcp_f32_e32 v122, v122
	v_rcp_f32_e32 v123, v123
	v_rcp_f32_e32 v126, v126
	v_rcp_f32_e32 v127, v127
	v_rcp_f32_e32 v128, v128
	v_rcp_f32_e32 v129, v129
	v_mul_f32_e32 v101, v101, v141
	v_mul_f32_e32 v105, v115, v105
	v_mul_f32_e32 v107, v107, v122
	v_mul_f32_e32 v111, v111, v123
	v_mul_f32_e32 v109, v109, v126
	v_mul_f32_e32 v113, v113, v127
	v_mul_f32_e32 v99, v99, v128
	v_mul_f32_e32 v103, v103, v129
	v_mul_f32_e32 v101, v100, v101
	v_mul_f32_e32 v105, v114, v105
	v_mul_f32_e32 v106, v106, v107
	v_mul_f32_e32 v107, v110, v111
	v_mul_f32_e32 v108, v108, v109
	v_mul_f32_e32 v109, v112, v113
	v_mul_f32_e32 v110, v98, v99
	v_mul_f32_e32 v102, v102, v103
	v_cvt_pk_bf16_f32 v98, v105, v106
	v_cvt_pk_bf16_f32 v99, v107, v108
	v_cvt_pk_bf16_f32 v100, v109, v110
	v_cvt_pk_bf16_f32 v101, v102, v101
	global_store_dwordx4 v[116:117], v[98:101], off
	s_nop 0
	s_nop 0
	v_mov_b32_e32 v99, v90
	v_mov_b32_e32 v90, v95
	v_mov_b32_e32 v95, v92
	v_mov_b32_e32 v92, v97
	v_mov_b32_e32 v97, v82
	v_mov_b32_e32 v82, v87
	v_mov_b32_e32 v87, v84
	v_mov_b32_e32 v84, v89
	v_mov_b32_e32 v98, v94
	v_mov_b32_e32 v94, v96
	v_mov_b32_e32 v96, v86
	v_mov_b32_e32 v86, v88
	v_or_b32_e32 v88, 48, v140
	v_mad_i64_i32 v[100:101], s[24:25], v104, s47, v[118:119]
	v_lshl_add_u64 v[100:101], v[100:101], 0, v[120:121]
	s_waitcnt vmcnt(7)
; __device__ __forceinline__ unsigned cvt_pk_bf16(float lo, float hi) { unsigned r; asm volatile("v_cvt_pk_bf16_f32 %0, %1, %2" : "=v"(r) : "v"(lo), "v"(hi)); return r; }
; __device__ __forceinline__ float silu_f(float x) { return x * sigmoid_f(x); }
;     __device__ __forceinline__ void operator()(const f32x4 (&acc)[2][2][4][2], const Unit& u, int wr, int wc, int fr, int fq) const {
;     ...
;             for (int m = 0; m < 4; ++m) {
;                 const int row = row0 + ai * HALF + m * 16;
;                 const float r = __builtin_amdgcn_rsqf(rss[row] * (1.f / 1024.f) + NEPS);
;                 float o[8];
; #pragma unroll
;                 for (int n = 0; n < 2; ++n)
; #pragma unroll
;                     for (int e = 0; e < 4; ++e) o[4 * n + e] = silu_f(acc[ai][0][m][n][e] * r) * (acc[ai][1][m][n][e] * r);
;                 u32x4 w; w.x = cvt_pk_bf16(o[0], o[1]); w.y = cvt_pk_bf16(o[2], o[3]); w.z = cvt_pk_bf16(o[4], o[5]); w.w = cvt_pk_bf16(o[6], o[7]);
;                 *(u32x4*)(O + (size_t)row * 2816 + col0) = w;
	v_mov_b32_e32 v102, v202
	v_fmamk_f32 v89, v102, 0x3a800000, v150
	v_rsq_f32_e32 v102, v89
	v_ashrrev_i32_e32 v89, 31, v88
	v_lshl_add_u64 v[104:105], v[88:89], 2, s[4:5]
	v_pk_mul_f32 v[84:85], v[84:85], v[102:103] op_sel_hi:[1,0]
	v_pk_mul_f32 v[98:99], v[98:99], v[102:103] op_sel_hi:[1,0]
	v_pk_mul_f32 v[90:91], v[90:91], v[102:103] op_sel_hi:[1,0]
	v_pk_mul_f32 v[94:95], v[94:95], v[102:103] op_sel_hi:[1,0]
	v_pk_mul_f32 v[92:93], v[92:93], v[102:103] op_sel_hi:[1,0]
	v_pk_mul_f32 v[96:97], v[96:97], v[102:103] op_sel_hi:[1,0]
	v_pk_mul_f32 v[82:83], v[82:83], v[102:103] op_sel_hi:[1,0]
	v_pk_mul_f32 v[86:87], v[86:87], v[102:103] op_sel_hi:[1,0]
	v_mul_f32_e32 v110, 0xbfb8aa3b, v85
	v_mul_f32_e32 v89, 0xbfb8aa3b, v99
	v_mul_f32_e32 v102, 0xbfb8aa3b, v91
	v_mul_f32_e32 v103, 0xbfb8aa3b, v95
	v_mul_f32_e32 v106, 0xbfb8aa3b, v93
	v_mul_f32_e32 v107, 0xbfb8aa3b, v97
	v_mul_f32_e32 v108, 0xbfb8aa3b, v83
	v_mul_f32_e32 v109, 0xbfb8aa3b, v87
	v_exp_f32_e32 v110, v110
	v_exp_f32_e32 v89, v89
	v_exp_f32_e32 v102, v102
	v_exp_f32_e32 v103, v103
	v_exp_f32_e32 v106, v106
	v_exp_f32_e32 v107, v107
	v_exp_f32_e32 v108, v108
	v_exp_f32_e32 v109, v109
	v_add_f32_e32 v110, 1.0, v110
	v_add_f32_e32 v89, 1.0, v89
	v_add_f32_e32 v102, 1.0, v102
	v_add_f32_e32 v103, 1.0, v103
	v_add_f32_e32 v106, 1.0, v106
	v_add_f32_e32 v107, 1.0, v107
	v_add_f32_e32 v108, 1.0, v108
	v_add_f32_e32 v109, 1.0, v109
	v_rcp_f32_e32 v110, v110
	v_rcp_f32_e32 v89, v89
	v_rcp_f32_e32 v102, v102
	v_rcp_f32_e32 v103, v103
	v_rcp_f32_e32 v106, v106
	v_rcp_f32_e32 v107, v107
	v_rcp_f32_e32 v108, v108
	v_rcp_f32_e32 v109, v109
	v_mul_f32_e32 v85, v85, v110
	v_mul_f32_e32 v89, v99, v89
	v_mul_f32_e32 v91, v91, v102
	v_mul_f32_e32 v95, v95, v103
	v_mul_f32_e32 v93, v93, v106
	v_mul_f32_e32 v97, v97, v107
	v_mul_f32_e32 v83, v83, v108
	v_mul_f32_e32 v87, v87, v109
	v_mul_f32_e32 v85, v84, v85
	v_mul_f32_e32 v89, v98, v89
	v_mul_f32_e32 v90, v90, v91
	v_mul_f32_e32 v91, v94, v95
	v_mul_f32_e32 v92, v92, v93
	v_mul_f32_e32 v93, v96, v97
	v_mul_f32_e32 v94, v82, v83
	v_mul_f32_e32 v86, v86, v87
	v_cvt_pk_bf16_f32 v82, v89, v90
	v_cvt_pk_bf16_f32 v83, v91, v92
	v_cvt_pk_bf16_f32 v84, v93, v94
	v_cvt_pk_bf16_f32 v85, v86, v85
	global_store_dwordx4 v[100:101], v[82:85], off
	s_nop 0
	s_nop 0
	v_mov_b32_e32 v82, v78
	v_mov_b32_e32 v78, v80
	v_mov_b32_e32 v80, v66
	v_mov_b32_e32 v66, v68
	v_mov_b32_e32 v83, v74
	v_mov_b32_e32 v74, v79
	v_mov_b32_e32 v79, v76
	v_mov_b32_e32 v76, v81
	v_mov_b32_e32 v81, v70
	v_mov_b32_e32 v70, v67
	v_mov_b32_e32 v67, v72
	v_mov_b32_e32 v72, v69
	s_waitcnt vmcnt(7)
	v_mov_b32_e32 v84, v203
	v_fmamk_f32 v68, v84, 0x3a800000, v150
	v_rsq_f32_e32 v68, v68
	v_mad_i64_i32 v[84:85], s[24:25], v88, s47, v[118:119]
	v_lshl_add_u64 v[84:85], v[84:85], 0, v[120:121]
	v_pk_mul_f32 v[82:83], v[82:83], v[68:69] op_sel_hi:[1,0]
	v_pk_mul_f32 v[74:75], v[74:75], v[68:69] op_sel_hi:[1,0]
	v_pk_mul_f32 v[78:79], v[78:79], v[68:69] op_sel_hi:[1,0]
	v_pk_mul_f32 v[76:77], v[76:77], v[68:69] op_sel_hi:[1,0]
	v_pk_mul_f32 v[80:81], v[80:81], v[68:69] op_sel_hi:[1,0]
	v_pk_mul_f32 v[70:71], v[70:71], v[68:69] op_sel_hi:[1,0]
	v_pk_mul_f32 v[66:67], v[66:67], v[68:69] op_sel_hi:[1,0]
	v_pk_mul_f32 v[68:69], v[72:73], v[68:69] op_sel_hi:[1,0]
	v_mul_f32_e32 v72, 0xbfb8aa3b, v83
	v_mul_f32_e32 v91, 0xbfb8aa3b, v69
	v_mul_f32_e32 v73, 0xbfb8aa3b, v75
	v_mul_f32_e32 v86, 0xbfb8aa3b, v79
	v_mul_f32_e32 v87, 0xbfb8aa3b, v77
	v_mul_f32_e32 v88, 0xbfb8aa3b, v81
	v_mul_f32_e32 v89, 0xbfb8aa3b, v71
	v_mul_f32_e32 v90, 0xbfb8aa3b, v67
	v_exp_f32_e32 v91, v91
	v_exp_f32_e32 v72, v72
	v_exp_f32_e32 v73, v73
	v_exp_f32_e32 v86, v86
	v_exp_f32_e32 v87, v87
	v_exp_f32_e32 v88, v88
	v_exp_f32_e32 v89, v89
	v_exp_f32_e32 v90, v90
	v_add_f32_e32 v91, 1.0, v91
	v_add_f32_e32 v72, 1.0, v72
	v_add_f32_e32 v73, 1.0, v73
	v_add_f32_e32 v86, 1.0, v86
	v_add_f32_e32 v87, 1.0, v87
	v_add_f32_e32 v88, 1.0, v88
	v_add_f32_e32 v89, 1.0, v89
	v_add_f32_e32 v90, 1.0, v90
	v_rcp_f32_e32 v91, v91
	v_rcp_f32_e32 v72, v72
	v_rcp_f32_e32 v73, v73
	v_rcp_f32_e32 v86, v86
	v_rcp_f32_e32 v87, v87
	v_rcp_f32_e32 v88, v88
	v_rcp_f32_e32 v89, v89
	v_rcp_f32_e32 v90, v90
	v_mul_f32_e32 v69, v69, v91
	v_mul_f32_e32 v72, v83, v72
	v_mul_f32_e32 v73, v75, v73
	v_mul_f32_e32 v75, v79, v86
	v_mul_f32_e32 v77, v77, v87
	v_mul_f32_e32 v79, v81, v88
	v_mul_f32_e32 v71, v71, v89
	v_mul_f32_e32 v67, v67, v90
	v_mul_f32_e32 v69, v68, v69
	v_mul_f32_e32 v72, v82, v72
	v_mul_f32_e32 v73, v74, v73
	v_mul_f32_e32 v74, v78, v75
	v_mul_f32_e32 v75, v76, v77
	v_mul_f32_e32 v76, v80, v79
	v_mul_f32_e32 v70, v70, v71
	v_mul_f32_e32 v71, v66, v67
	v_cvt_pk_bf16_f32 v66, v72, v73
	v_cvt_pk_bf16_f32 v67, v74, v75
	v_cvt_pk_bf16_f32 v68, v76, v70
	v_cvt_pk_bf16_f32 v69, v71, v69
	global_store_dwordx4 v[84:85], v[66:69], off
	s_nop 0
	s_nop 0
	v_mov_b32_e32 v66, v62
	v_mov_b32_e32 v62, v64
	v_mov_b32_e32 v64, v50
	v_mov_b32_e32 v50, v52
	v_mov_b32_e32 v67, v58
	v_mov_b32_e32 v58, v63
	v_mov_b32_e32 v63, v60
	v_mov_b32_e32 v60, v65
	v_mov_b32_e32 v65, v54
	v_mov_b32_e32 v54, v51
	v_mov_b32_e32 v51, v56
	v_mov_b32_e32 v56, v53
	v_add_u32_e32 v53, 0x80, v140
	s_waitcnt vmcnt(7)
; __device__ __forceinline__ unsigned cvt_pk_bf16(float lo, float hi) { unsigned r; asm volatile("v_cvt_pk_bf16_f32 %0, %1, %2" : "=v"(r) : "v"(lo), "v"(hi)); return r; }
; __device__ __forceinline__ float silu_f(float x) { return x * sigmoid_f(x); }
;     __device__ __forceinline__ void operator()(const f32x4 (&acc)[2][2][4][2], const Unit& u, int wr, int wc, int fr, int fq) const {
;         const int row0 = u.pm * BM + wr * 64 + fr, col0 = u.pn * 128 + wc * 32 + 8 * fq;
; #pragma unroll
;         for (int ai = 0; ai < 2; ++ai)
; #pragma unroll
;             for (int m = 0; m < 4; ++m) {
;                 const int row = row0 + ai * HALF + m * 16;
;                 const float r = __builtin_amdgcn_rsqf(rss[row] * (1.f / 1024.f) + NEPS);
;                 float o[8];
; #pragma unroll
;                 for (int n = 0; n < 2; ++n)
; #pragma unroll
;                     for (int e = 0; e < 4; ++e) o[4 * n + e] = silu_f(acc[ai][0][m][n][e] * r) * (acc[ai][1][m][n][e] * r);
;                 u32x4 w; w.x = cvt_pk_bf16(o[0], o[1]); w.y = cvt_pk_bf16(o[2], o[3]); w.z = cvt_pk_bf16(o[4], o[5]); w.w = cvt_pk_bf16(o[6], o[7]);
;                 *(u32x4*)(O + (size_t)row * 2816 + col0) = w;
	v_mov_b32_e32 v68, v204
	v_fmamk_f32 v52, v68, 0x3a800000, v150
	v_rsq_f32_e32 v52, v52
	v_mad_i64_i32 v[68:69], s[24:25], v53, s47, v[118:119]
	v_lshl_add_u64 v[68:69], v[68:69], 0, v[120:121]
	v_pk_mul_f32 v[66:67], v[66:67], v[52:53] op_sel_hi:[1,0]
	v_pk_mul_f32 v[58:59], v[58:59], v[52:53] op_sel_hi:[1,0]
	v_pk_mul_f32 v[62:63], v[62:63], v[52:53] op_sel_hi:[1,0]
	v_pk_mul_f32 v[60:61], v[60:61], v[52:53] op_sel_hi:[1,0]
	v_pk_mul_f32 v[64:65], v[64:65], v[52:53] op_sel_hi:[1,0]
	v_pk_mul_f32 v[54:55], v[54:55], v[52:53] op_sel_hi:[1,0]
	v_pk_mul_f32 v[50:51], v[50:51], v[52:53] op_sel_hi:[1,0]
	v_pk_mul_f32 v[52:53], v[56:57], v[52:53] op_sel_hi:[1,0]
	v_mul_f32_e32 v56, 0xbfb8aa3b, v67
	v_mul_f32_e32 v75, 0xbfb8aa3b, v53
	v_mul_f32_e32 v57, 0xbfb8aa3b, v59
	v_mul_f32_e32 v70, 0xbfb8aa3b, v63
	v_mul_f32_e32 v71, 0xbfb8aa3b, v61
	v_mul_f32_e32 v72, 0xbfb8aa3b, v65
	v_mul_f32_e32 v73, 0xbfb8aa3b, v55
	v_mul_f32_e32 v74, 0xbfb8aa3b, v51
	v_exp_f32_e32 v75, v75
	v_exp_f32_e32 v56, v56
	v_exp_f32_e32 v57, v57
	v_exp_f32_e32 v70, v70
	v_exp_f32_e32 v71, v71
	v_exp_f32_e32 v72, v72
	v_exp_f32_e32 v73, v73
	v_exp_f32_e32 v74, v74
	v_add_f32_e32 v75, 1.0, v75
	v_add_f32_e32 v56, 1.0, v56
	v_add_f32_e32 v57, 1.0, v57
	v_add_f32_e32 v70, 1.0, v70
	v_add_f32_e32 v71, 1.0, v71
	v_add_f32_e32 v72, 1.0, v72
	v_add_f32_e32 v73, 1.0, v73
	v_add_f32_e32 v74, 1.0, v74
	v_rcp_f32_e32 v75, v75
	v_rcp_f32_e32 v56, v56
	v_rcp_f32_e32 v57, v57
	v_rcp_f32_e32 v70, v70
	v_rcp_f32_e32 v71, v71
	v_rcp_f32_e32 v72, v72
	v_rcp_f32_e32 v73, v73
	v_rcp_f32_e32 v74, v74
	v_mul_f32_e32 v53, v53, v75
	v_mul_f32_e32 v56, v67, v56
	v_mul_f32_e32 v57, v59, v57
	v_mul_f32_e32 v59, v63, v70
	v_mul_f32_e32 v61, v61, v71
	v_mul_f32_e32 v63, v65, v72
	v_mul_f32_e32 v55, v55, v73
	v_mul_f32_e32 v51, v51, v74
	v_mul_f32_e32 v53, v52, v53
	v_mul_f32_e32 v56, v66, v56
	v_mul_f32_e32 v57, v58, v57
	v_mul_f32_e32 v58, v62, v59
	v_mul_f32_e32 v59, v60, v61
	v_mul_f32_e32 v60, v64, v63
	v_mul_f32_e32 v54, v54, v55
	v_mul_f32_e32 v55, v50, v51
	v_cvt_pk_bf16_f32 v50, v56, v57
	v_cvt_pk_bf16_f32 v51, v58, v59
	v_cvt_pk_bf16_f32 v52, v60, v54
	v_cvt_pk_bf16_f32 v53, v55, v53
	global_store_dwordx4 v[68:69], v[50:53], off
	s_nop 0
	s_nop 0
	v_mov_b32_e32 v50, v46
	v_mov_b32_e32 v46, v48
	v_mov_b32_e32 v48, v34
	v_mov_b32_e32 v34, v36
	v_mov_b32_e32 v51, v42
	v_mov_b32_e32 v42, v47
	v_mov_b32_e32 v47, v44
	v_mov_b32_e32 v44, v49
	v_mov_b32_e32 v49, v38
	v_mov_b32_e32 v38, v35
	v_mov_b32_e32 v35, v40
	v_mov_b32_e32 v40, v37
	v_add_u32_e32 v37, 0x90, v140
	s_waitcnt vmcnt(7)
	v_mov_b32_e32 v52, v205
	v_fmamk_f32 v36, v52, 0x3a800000, v150
	v_rsq_f32_e32 v36, v36
	v_mad_i64_i32 v[52:53], s[24:25], v37, s47, v[118:119]
	v_lshl_add_u64 v[52:53], v[52:53], 0, v[120:121]
	v_pk_mul_f32 v[50:51], v[50:51], v[36:37] op_sel_hi:[1,0]
	v_pk_mul_f32 v[42:43], v[42:43], v[36:37] op_sel_hi:[1,0]
	v_pk_mul_f32 v[46:47], v[46:47], v[36:37] op_sel_hi:[1,0]
	v_pk_mul_f32 v[44:45], v[44:45], v[36:37] op_sel_hi:[1,0]
	v_pk_mul_f32 v[48:49], v[48:49], v[36:37] op_sel_hi:[1,0]
	v_pk_mul_f32 v[38:39], v[38:39], v[36:37] op_sel_hi:[1,0]
	v_pk_mul_f32 v[34:35], v[34:35], v[36:37] op_sel_hi:[1,0]
	v_pk_mul_f32 v[36:37], v[40:41], v[36:37] op_sel_hi:[1,0]
	v_mul_f32_e32 v40, 0xbfb8aa3b, v51
	v_mul_f32_e32 v59, 0xbfb8aa3b, v37
	v_mul_f32_e32 v41, 0xbfb8aa3b, v43
	v_mul_f32_e32 v54, 0xbfb8aa3b, v47
	v_mul_f32_e32 v55, 0xbfb8aa3b, v45
	v_mul_f32_e32 v56, 0xbfb8aa3b, v49
	v_mul_f32_e32 v57, 0xbfb8aa3b, v39
	v_mul_f32_e32 v58, 0xbfb8aa3b, v35
	v_exp_f32_e32 v59, v59
	v_exp_f32_e32 v40, v40
	v_exp_f32_e32 v41, v41
	v_exp_f32_e32 v54, v54
	v_exp_f32_e32 v55, v55
	v_exp_f32_e32 v56, v56
	v_exp_f32_e32 v57, v57
	v_exp_f32_e32 v58, v58
	v_add_f32_e32 v59, 1.0, v59
	v_add_f32_e32 v40, 1.0, v40
	v_add_f32_e32 v41, 1.0, v41
	v_add_f32_e32 v54, 1.0, v54
	v_add_f32_e32 v55, 1.0, v55
	v_add_f32_e32 v56, 1.0, v56
	v_add_f32_e32 v57, 1.0, v57
	v_add_f32_e32 v58, 1.0, v58
	v_rcp_f32_e32 v59, v59
	v_rcp_f32_e32 v40, v40
	v_rcp_f32_e32 v41, v41
	v_rcp_f32_e32 v54, v54
	v_rcp_f32_e32 v55, v55
	v_rcp_f32_e32 v56, v56
	v_rcp_f32_e32 v57, v57
	v_rcp_f32_e32 v58, v58
	v_mul_f32_e32 v37, v37, v59
	v_mul_f32_e32 v40, v51, v40
	v_mul_f32_e32 v41, v43, v41
	v_mul_f32_e32 v43, v47, v54
	v_mul_f32_e32 v45, v45, v55
	v_mul_f32_e32 v47, v49, v56
	v_mul_f32_e32 v39, v39, v57
	v_mul_f32_e32 v35, v35, v58
	v_mul_f32_e32 v37, v36, v37
	v_mul_f32_e32 v40, v50, v40
	v_mul_f32_e32 v41, v42, v41
	v_mul_f32_e32 v42, v46, v43
	v_mul_f32_e32 v43, v44, v45
	v_mul_f32_e32 v44, v48, v47
	v_mul_f32_e32 v38, v38, v39
	v_mul_f32_e32 v39, v34, v35
	v_cvt_pk_bf16_f32 v34, v40, v41
	v_cvt_pk_bf16_f32 v35, v42, v43
	v_cvt_pk_bf16_f32 v36, v44, v38
	v_cvt_pk_bf16_f32 v37, v39, v37
	global_store_dwordx4 v[52:53], v[34:37], off
	s_nop 0
	s_nop 0
	v_mov_b32_e32 v34, v30
	v_mov_b32_e32 v30, v32
	v_mov_b32_e32 v32, v18
	v_mov_b32_e32 v18, v20
	v_mov_b32_e32 v35, v26
	v_mov_b32_e32 v26, v31
	v_mov_b32_e32 v31, v28
	v_mov_b32_e32 v28, v33
	v_mov_b32_e32 v33, v22
	v_mov_b32_e32 v22, v19
	v_mov_b32_e32 v19, v24
	v_mov_b32_e32 v24, v21
	v_add_u32_e32 v21, 0xa0, v140
	s_waitcnt vmcnt(7)
; __device__ __forceinline__ unsigned cvt_pk_bf16(float lo, float hi) { unsigned r; asm volatile("v_cvt_pk_bf16_f32 %0, %1, %2" : "=v"(r) : "v"(lo), "v"(hi)); return r; }
; __device__ __forceinline__ float silu_f(float x) { return x * sigmoid_f(x); }
; #define PG8_BAR __builtin_amdgcn_s_barrier()
;     __device__ __forceinline__ void operator()(const f32x4 (&acc)[2][2][4][2], const Unit& u, int wr, int wc, int fr, int fq) const {
;         const int row0 = u.pm * BM + wr * 64 + fr, col0 = u.pn * 128 + wc * 32 + 8 * fq;
; #pragma unroll
;         for (int ai = 0; ai < 2; ++ai)
; #pragma unroll
;             for (int m = 0; m < 4; ++m) {
;                 const int row = row0 + ai * HALF + m * 16;
;                 const float r = __builtin_amdgcn_rsqf(rss[row] * (1.f / 1024.f) + NEPS);
;                 float o[8];
; #pragma unroll
;                 for (int n = 0; n < 2; ++n)
; #pragma unroll
;                     for (int e = 0; e < 4; ++e) o[4 * n + e] = silu_f(acc[ai][0][m][n][e] * r) * (acc[ai][1][m][n][e] * r);
;                 u32x4 w; w.x = cvt_pk_bf16(o[0], o[1]); w.y = cvt_pk_bf16(o[2], o[3]); w.z = cvt_pk_bf16(o[4], o[5]); w.w = cvt_pk_bf16(o[6], o[7]);
;                 *(u32x4*)(O + (size_t)row * 2816 + col0) = w;
; template <class Epi, class Sched, bool ALIGN_EPI = false, bool SP2 = false>
; __device__ __forceinline__ void gemm_phase(PG8_LAS unsigned char* lds, const Gemm g, const Sched& S, const Epi& E) {
;     ...
;         if (!has_next) break;
; #pragma unroll
;         for (int a = 0; a < 2; ++a)
; #pragma unroll
;             for (int b = 0; b < 2; ++b)
; #pragma unroll
;                 for (int m = 0; m < 4; ++m)
; #pragma unroll
;                     for (int n = 0; n < 2; ++n) acc[a][b][m][n] = (f32x4){0.f, 0.f, 0.f, 0.f};
;         cur = nxt; cA = nA; cB = nB; ++ui;
;         if constexpr (ALIGN_EPI) { if (wr == 1) PG8_BAR; }
	v_mov_b32_e32 v36, v206
	v_fmamk_f32 v20, v36, 0x3a800000, v150
	v_rsq_f32_e32 v20, v20
	v_mad_i64_i32 v[36:37], s[24:25], v21, s47, v[118:119]
	v_lshl_add_u64 v[36:37], v[36:37], 0, v[120:121]
	v_pk_mul_f32 v[34:35], v[34:35], v[20:21] op_sel_hi:[1,0]
	v_pk_mul_f32 v[26:27], v[26:27], v[20:21] op_sel_hi:[1,0]
	v_pk_mul_f32 v[30:31], v[30:31], v[20:21] op_sel_hi:[1,0]
	v_pk_mul_f32 v[28:29], v[28:29], v[20:21] op_sel_hi:[1,0]
	v_pk_mul_f32 v[32:33], v[32:33], v[20:21] op_sel_hi:[1,0]
	v_pk_mul_f32 v[22:23], v[22:23], v[20:21] op_sel_hi:[1,0]
	v_pk_mul_f32 v[18:19], v[18:19], v[20:21] op_sel_hi:[1,0]
	v_pk_mul_f32 v[20:21], v[24:25], v[20:21] op_sel_hi:[1,0]
	v_mul_f32_e32 v24, 0xbfb8aa3b, v35
	v_mul_f32_e32 v43, 0xbfb8aa3b, v21
	v_mul_f32_e32 v25, 0xbfb8aa3b, v27
	v_mul_f32_e32 v38, 0xbfb8aa3b, v31
	v_mul_f32_e32 v39, 0xbfb8aa3b, v29
	v_mul_f32_e32 v40, 0xbfb8aa3b, v33
	v_mul_f32_e32 v41, 0xbfb8aa3b, v23
	v_mul_f32_e32 v42, 0xbfb8aa3b, v19
	v_exp_f32_e32 v43, v43
	v_exp_f32_e32 v24, v24
	v_exp_f32_e32 v25, v25
	v_exp_f32_e32 v38, v38
	v_exp_f32_e32 v39, v39
	v_exp_f32_e32 v40, v40
	v_exp_f32_e32 v41, v41
	v_exp_f32_e32 v42, v42
	v_add_f32_e32 v43, 1.0, v43
	v_add_f32_e32 v24, 1.0, v24
	v_add_f32_e32 v25, 1.0, v25
	v_add_f32_e32 v38, 1.0, v38
	v_add_f32_e32 v39, 1.0, v39
	v_add_f32_e32 v40, 1.0, v40
	v_add_f32_e32 v41, 1.0, v41
	v_add_f32_e32 v42, 1.0, v42
	v_rcp_f32_e32 v43, v43
	v_rcp_f32_e32 v24, v24
	v_rcp_f32_e32 v25, v25
	v_rcp_f32_e32 v38, v38
	v_rcp_f32_e32 v39, v39
	v_rcp_f32_e32 v40, v40
	v_rcp_f32_e32 v41, v41
	v_rcp_f32_e32 v42, v42
	v_mul_f32_e32 v21, v21, v43
	v_mul_f32_e32 v24, v35, v24
	v_mul_f32_e32 v25, v27, v25
	v_mul_f32_e32 v27, v31, v38
	v_mul_f32_e32 v29, v29, v39
	v_mul_f32_e32 v31, v33, v40
	v_mul_f32_e32 v23, v23, v41
	v_mul_f32_e32 v19, v19, v42
	v_mul_f32_e32 v21, v20, v21
	v_mul_f32_e32 v24, v34, v24
	v_mul_f32_e32 v25, v26, v25
	v_mul_f32_e32 v26, v30, v27
	v_mul_f32_e32 v27, v28, v29
	v_mul_f32_e32 v28, v32, v31
	v_mul_f32_e32 v22, v22, v23
	v_mul_f32_e32 v23, v18, v19
	v_cvt_pk_bf16_f32 v18, v24, v25
	v_cvt_pk_bf16_f32 v19, v26, v27
	v_cvt_pk_bf16_f32 v20, v28, v22
	v_cvt_pk_bf16_f32 v21, v23, v21
	global_store_dwordx4 v[36:37], v[18:21], off
	s_nop 0
	s_nop 0
	v_mov_b32_e32 v18, v14
	v_mov_b32_e32 v14, v16
	v_mov_b32_e32 v16, v2
	v_mov_b32_e32 v2, v4
	v_mov_b32_e32 v19, v10
	v_mov_b32_e32 v10, v15
	v_mov_b32_e32 v15, v12
	v_mov_b32_e32 v12, v17
	v_mov_b32_e32 v17, v6
	v_mov_b32_e32 v6, v3
	v_mov_b32_e32 v3, v8
	v_mov_b32_e32 v8, v5
	v_add_u32_e32 v5, 0xb0, v140
	s_waitcnt vmcnt(7)
	v_mov_b32_e32 v20, v207
	v_fmamk_f32 v4, v20, 0x3a800000, v150
	v_rsq_f32_e32 v4, v4
	v_mad_i64_i32 v[20:21], s[24:25], v5, s47, v[118:119]
	v_lshl_add_u64 v[20:21], v[20:21], 0, v[120:121]
	v_pk_mul_f32 v[18:19], v[18:19], v[4:5] op_sel_hi:[1,0]
	v_pk_mul_f32 v[10:11], v[10:11], v[4:5] op_sel_hi:[1,0]
	v_pk_mul_f32 v[14:15], v[14:15], v[4:5] op_sel_hi:[1,0]
	v_pk_mul_f32 v[12:13], v[12:13], v[4:5] op_sel_hi:[1,0]
	v_pk_mul_f32 v[16:17], v[16:17], v[4:5] op_sel_hi:[1,0]
	v_pk_mul_f32 v[6:7], v[6:7], v[4:5] op_sel_hi:[1,0]
	v_pk_mul_f32 v[2:3], v[2:3], v[4:5] op_sel_hi:[1,0]
	v_pk_mul_f32 v[4:5], v[8:9], v[4:5] op_sel_hi:[1,0]
	v_mul_f32_e32 v8, 0xbfb8aa3b, v19
	v_mul_f32_e32 v27, 0xbfb8aa3b, v5
	v_mul_f32_e32 v9, 0xbfb8aa3b, v11
	v_mul_f32_e32 v22, 0xbfb8aa3b, v15
	v_mul_f32_e32 v23, 0xbfb8aa3b, v13
	v_mul_f32_e32 v24, 0xbfb8aa3b, v17
	v_mul_f32_e32 v25, 0xbfb8aa3b, v7
	v_mul_f32_e32 v26, 0xbfb8aa3b, v3
	v_exp_f32_e32 v27, v27
	v_exp_f32_e32 v8, v8
	v_exp_f32_e32 v9, v9
	v_exp_f32_e32 v22, v22
	v_exp_f32_e32 v23, v23
	v_exp_f32_e32 v24, v24
	v_exp_f32_e32 v25, v25
	v_exp_f32_e32 v26, v26
	v_add_f32_e32 v27, 1.0, v27
	v_add_f32_e32 v8, 1.0, v8
	v_add_f32_e32 v9, 1.0, v9
	v_add_f32_e32 v22, 1.0, v22
	v_add_f32_e32 v23, 1.0, v23
	v_add_f32_e32 v24, 1.0, v24
	v_add_f32_e32 v25, 1.0, v25
	v_add_f32_e32 v26, 1.0, v26
	v_rcp_f32_e32 v27, v27
	v_rcp_f32_e32 v8, v8
	v_rcp_f32_e32 v9, v9
	v_rcp_f32_e32 v22, v22
	v_rcp_f32_e32 v23, v23
	v_rcp_f32_e32 v24, v24
	v_rcp_f32_e32 v25, v25
	v_rcp_f32_e32 v26, v26
	v_mul_f32_e32 v5, v5, v27
	v_mul_f32_e32 v8, v19, v8
	v_mul_f32_e32 v9, v11, v9
	v_mul_f32_e32 v11, v15, v22
	v_mul_f32_e32 v13, v13, v23
	v_mul_f32_e32 v15, v17, v24
	v_mul_f32_e32 v7, v7, v25
	v_mul_f32_e32 v3, v3, v26
	v_mul_f32_e32 v5, v4, v5
	v_mul_f32_e32 v8, v18, v8
	v_mul_f32_e32 v9, v10, v9
	v_mul_f32_e32 v10, v14, v11
	v_mul_f32_e32 v11, v12, v13
	v_mul_f32_e32 v12, v16, v15
	v_mul_f32_e32 v6, v6, v7
	v_mul_f32_e32 v7, v2, v3
	v_cvt_pk_bf16_f32 v2, v8, v9
	v_cvt_pk_bf16_f32 v3, v10, v11
	v_cvt_pk_bf16_f32 v4, v12, v6
	v_cvt_pk_bf16_f32 v5, v7, v5
	global_store_dwordx4 v[20:21], v[2:5], off
	s_cbranch_vccnz .LBB0_127
	s_andn2_b64 vcc, exec, s[10:11]
	s_cbranch_vccnz .LBB0_126
	s_barrier
	s_branch .LBB0_126

; #define PG8_STAGE(bufoff, gbase, voff) do { _Pragma("unroll") for (int _i = 0; _i < 2; ++_i) \
;         __builtin_amdgcn_global_load_lds((const unsigned*)((const char*)(gbase) + (voff)[_i]), (PG8_LAS unsigned*)(lds + (bufoff) + ldsw + _i * 8192), 16, 0, 0); } while (0)
; #define PG8_LDA(dst, b, h) do { _Pragma("unroll") for (int m = 0; m < 4; ++m) _Pragma("unroll") for (int k = 0; k < 2; ++k) dst[m][k] = *(const PG8_LAS bf16x8*)(lds + PG8_SA(b, h) + aoff + m * 2048 + k * 1024); } while (0)
; #define PG8_LDB(dst, b, h) do { _Pragma("unroll") for (int n = 0; n < 2; ++n) _Pragma("unroll") for (int k = 0; k < 2; ++k) dst[n][k] = *(const PG8_LAS bf16x8*)(lds + PG8_SB(b, h) + boff + n * 2048 + k * 1024); } while (0)
; #define PG8_MMA(ai, bj, At, Bt) do { __builtin_amdgcn_s_setprio(1); _Pragma("unroll") for (int m = 0; m < 4; ++m) _Pragma("unroll") for (int n = 0; n < 2; ++n) _Pragma("unroll") for (int k = 0; k < 2; ++k) \
;         acc[ai][bj][m][n] = __builtin_amdgcn_mfma_f32_16x16x32_bf16(Bt[n][k], At[m][k], acc[ai][bj][m][n], 0, 0, 0); __builtin_amdgcn_s_setprio(0); } while (0)
; #define PG8_WAIT_V(n) asm volatile("s_waitcnt vmcnt(" #n ")" ::: "memory")
; #define PG8_WAIT_L(n) asm volatile("s_waitcnt lgkmcnt(" #n ")" ::: "memory")
; #define PG8_BAR __builtin_amdgcn_s_barrier()
; #define PG8_SCHED __builtin_amdgcn_sched_barrier(0)
; template <class Epi, class Sched, bool ALIGN_EPI = false, bool SP2 = false>
; __device__ __forceinline__ void gemm_phase(PG8_LAS unsigned char* lds, const Gemm g, const Sched& S, const Epi& E) {
;     ...
;             PG8_LDB(B0, 0, 0); PG8_LDB(B1, 0, 1); PG8_SCHED; PG8_LDA(At, 0, 0); PG8_STAGE(PG8_SA(1, 1), a1 + hstep, voffA);
;             PG8_WAIT_V(8); PG8_WAIT_L(0); PG8_BAR; PG8_MMA(0, 0, At, B0); PG8_MMA(0, 1, At, B1); PG8_BAR; PG8_SCHED;
;             PG8_LDA(At, 0, 1); PG8_STAGE(PG8_SB(0, 0), b2, voffB); PG8_STAGE(PG8_SB(0, 1), b2 + hstep, voffB); PG8_STAGE(PG8_SA(0, 0), a2, voffA);
.LBB0_1489:
	ds_read_b128 v[140:143], v146
	ds_read_b128 v[150:153], v146 offset:1024
	ds_read_b128 v[154:157], v146 offset:2048
	ds_read_b128 v[158:161], v146 offset:3072
	ds_read_b128 v[162:165], v147
	ds_read_b128 v[166:169], v147 offset:1024
	ds_read_b128 v[170:173], v147 offset:2048
	ds_read_b128 v[174:177], v147 offset:3072
	s_add_u32 s38, s36, 0xfffc0080
	s_addc_u32 s39, s37, -1
	s_cmp_eq_u32 s68, 12
	s_cselect_b32 s41, s29, s39
	s_cselect_b32 s40, s64, s38
	s_cselect_b32 s39, s27, s67
	s_cselect_b32 s38, s65, s66
	v_lshl_add_u64 v[210:211], s[36:37], 0, v[134:135]
	s_add_i32 m0, s45, 0xc000
	ds_read_b128 v[178:181], v148
	ds_read_b128 v[182:185], v148 offset:1024
	ds_read_b128 v[186:189], v148 offset:2048
	ds_read_b128 v[190:193], v148 offset:3072
	ds_read_b128 v[194:197], v148 offset:4096
	ds_read_b128 v[198:201], v148 offset:5120
	ds_read_b128 v[202:205], v148 offset:6144
	ds_read_b128 v[206:209], v148 offset:7168
	global_load_lds_dwordx4 v[210:211], off
	v_lshl_add_u64 v[210:211], s[36:37], 0, v[136:137]
	s_add_i32 m0, s45, 0xe000
	s_nop 0
	global_load_lds_dwordx4 v[210:211], off
	s_waitcnt vmcnt(8)
	s_waitcnt lgkmcnt(0)
	s_barrier
	s_setprio 1
	s_waitcnt lgkmcnt(0)
	v_mfma_f32_16x16x32_bf16 v[118:121], v[140:143], v[178:181], v[118:121]
	v_mfma_f32_16x16x32_bf16 v[114:117], v[154:157], v[178:181], v[114:117]
	v_mfma_f32_16x16x32_bf16 v[106:109], v[140:143], v[186:189], v[106:109]
	v_mfma_f32_16x16x32_bf16 v[98:101], v[154:157], v[186:189], v[98:101]
	v_mfma_f32_16x16x32_bf16 v[90:93], v[140:143], v[194:197], v[90:93]
	v_mfma_f32_16x16x32_bf16 v[82:85], v[154:157], v[194:197], v[82:85]
	v_mfma_f32_16x16x32_bf16 v[74:77], v[140:143], v[202:205], v[74:77]
	v_mfma_f32_16x16x32_bf16 v[70:73], v[154:157], v[202:205], v[70:73]
	v_mfma_f32_16x16x32_bf16 v[118:121], v[150:153], v[182:185], v[118:121]
	v_mfma_f32_16x16x32_bf16 v[114:117], v[158:161], v[182:185], v[114:117]
	v_mfma_f32_16x16x32_bf16 v[106:109], v[150:153], v[190:193], v[106:109]
	v_mfma_f32_16x16x32_bf16 v[98:101], v[158:161], v[190:193], v[98:101]
	v_mfma_f32_16x16x32_bf16 v[90:93], v[150:153], v[198:201], v[90:93]
	v_mfma_f32_16x16x32_bf16 v[82:85], v[158:161], v[198:201], v[82:85]
	v_mfma_f32_16x16x32_bf16 v[74:77], v[150:153], v[206:209], v[74:77]
	v_mfma_f32_16x16x32_bf16 v[70:73], v[158:161], v[206:209], v[70:73]
	s_setprio 0
	s_setprio 1
	v_mfma_f32_16x16x32_bf16 v[126:129], v[162:165], v[178:181], v[126:129]
	v_mfma_f32_16x16x32_bf16 v[122:125], v[170:173], v[178:181], v[122:125]
	v_mfma_f32_16x16x32_bf16 v[110:113], v[162:165], v[186:189], v[110:113]
	v_mfma_f32_16x16x32_bf16 v[102:105], v[170:173], v[186:189], v[102:105]
	v_mfma_f32_16x16x32_bf16 v[94:97], v[162:165], v[194:197], v[94:97]
	v_mfma_f32_16x16x32_bf16 v[86:89], v[170:173], v[194:197], v[86:89]
	v_mfma_f32_16x16x32_bf16 v[78:81], v[162:165], v[202:205], v[78:81]
	v_mfma_f32_16x16x32_bf16 v[66:69], v[170:173], v[202:205], v[66:69]
	v_mfma_f32_16x16x32_bf16 v[126:129], v[166:169], v[182:185], v[126:129]
	v_mfma_f32_16x16x32_bf16 v[122:125], v[174:177], v[182:185], v[122:125]
	v_mfma_f32_16x16x32_bf16 v[110:113], v[166:169], v[190:193], v[110:113]
	v_mfma_f32_16x16x32_bf16 v[102:105], v[174:177], v[190:193], v[102:105]
	v_mfma_f32_16x16x32_bf16 v[94:97], v[166:169], v[198:201], v[94:97]
	v_mfma_f32_16x16x32_bf16 v[86:89], v[174:177], v[198:201], v[86:89]
	v_mfma_f32_16x16x32_bf16 v[78:81], v[166:169], v[206:209], v[78:81]
	v_mfma_f32_16x16x32_bf16 v[66:69], v[174:177], v[206:209], v[66:69]
	s_setprio 0
	s_barrier
	s_add_i32 s69, s6, s43
	v_lshl_add_u64 v[210:211], s[38:39], 0, v[132:133]
	s_mov_b32 m0, s69
	ds_read_b128 v[178:181], v148 offset:16384
	ds_read_b128 v[182:185], v148 offset:17408
	ds_read_b128 v[186:189], v148 offset:18432
	ds_read_b128 v[190:193], v148 offset:19456
	ds_read_b128 v[194:197], v148 offset:20480
	ds_read_b128 v[198:201], v148 offset:21504
	ds_read_b128 v[202:205], v148 offset:22528
	ds_read_b128 v[206:209], v148 offset:23552
	global_load_lds_dwordx4 v[210:211], off
	s_add_i32 m0, s69, 0x2000
	s_add_u32 s70, s38, 0x40000
	v_lshl_add_u64 v[212:213], s[38:39], 0, v[130:131]
	s_addc_u32 s71, s39, 0
	s_add_i32 s69, s60, s43
	global_load_lds_dwordx4 v[212:213], off
	v_lshl_add_u64 v[214:215], s[70:71], 0, v[132:133]
	s_mov_b32 m0, s69
	v_lshl_add_u64 v[216:217], s[40:41], 0, v[130:131]
	global_load_lds_dwordx4 v[214:215], off
	v_lshl_add_u64 v[214:215], s[70:71], 0, v[130:131]
	s_add_i32 m0, s69, 0x2000
	s_nop 0
	global_load_lds_dwordx4 v[214:215], off
	v_lshl_add_u64 v[214:215], s[40:41], 0, v[132:133]
	s_mov_b32 m0, s45
	s_nop 0
	global_load_lds_dwordx4 v[214:215], off
	s_mov_b32 m0, s46
	s_nop 0
	global_load_lds_dwordx4 v[216:217], off
	s_waitcnt vmcnt(8)
	s_waitcnt lgkmcnt(0)
	s_barrier
; #define PG8_STAGE(bufoff, gbase, voff) do { _Pragma("unroll") for (int _i = 0; _i < 2; ++_i) \
;         __builtin_amdgcn_global_load_lds((const unsigned*)((const char*)(gbase) + (voff)[_i]), (PG8_LAS unsigned*)(lds + (bufoff) + ldsw + _i * 8192), 16, 0, 0); } while (0)
; #define PG8_LDA(dst, b, h) do { _Pragma("unroll") for (int m = 0; m < 4; ++m) _Pragma("unroll") for (int k = 0; k < 2; ++k) dst[m][k] = *(const PG8_LAS bf16x8*)(lds + PG8_SA(b, h) + aoff + m * 2048 + k * 1024); } while (0)
; #define PG8_LDB(dst, b, h) do { _Pragma("unroll") for (int n = 0; n < 2; ++n) _Pragma("unroll") for (int k = 0; k < 2; ++k) dst[n][k] = *(const PG8_LAS bf16x8*)(lds + PG8_SB(b, h) + boff + n * 2048 + k * 1024); } while (0)
; #define PG8_MMA(ai, bj, At, Bt) do { __builtin_amdgcn_s_setprio(1); _Pragma("unroll") for (int m = 0; m < 4; ++m) _Pragma("unroll") for (int n = 0; n < 2; ++n) _Pragma("unroll") for (int k = 0; k < 2; ++k) \
;         acc[ai][bj][m][n] = __builtin_amdgcn_mfma_f32_16x16x32_bf16(Bt[n][k], At[m][k], acc[ai][bj][m][n], 0, 0, 0); __builtin_amdgcn_s_setprio(0); } while (0)
; #define PG8_WAIT_V(n) asm volatile("s_waitcnt vmcnt(" #n ")" ::: "memory")
; #define PG8_WAIT_L(n) asm volatile("s_waitcnt lgkmcnt(" #n ")" ::: "memory")
; #define PG8_BAR __builtin_amdgcn_s_barrier()
; #define PG8_SCHED __builtin_amdgcn_sched_barrier(0)
; template <class Epi, class Sched, bool ALIGN_EPI = false, bool SP2 = false>
; __device__ __forceinline__ void gemm_phase(PG8_LAS unsigned char* lds, const Gemm g, const Sched& S, const Epi& E) {
;     ...
;             PG8_WAIT_V(8); PG8_WAIT_L(0); PG8_BAR; PG8_MMA(1, 0, At, B0); PG8_MMA(1, 1, At, B1); PG8_BAR; PG8_SCHED;
;             PG8_LDB(B0, 1, 0); PG8_LDB(B1, 1, 1); PG8_SCHED; PG8_LDA(At, 1, 0); PG8_STAGE(PG8_SA(0, 1), a2 + hstep, voffA);
;             PG8_WAIT_V(8); PG8_WAIT_L(0); PG8_BAR; PG8_MMA(0, 0, At, B0); PG8_MMA(0, 1, At, B1); PG8_BAR; PG8_SCHED;
	s_setprio 1
	s_waitcnt lgkmcnt(0)
	v_mfma_f32_16x16x32_bf16 v[58:61], v[140:143], v[178:181], v[58:61]
	v_mfma_f32_16x16x32_bf16 v[54:57], v[154:157], v[178:181], v[54:57]
	v_mfma_f32_16x16x32_bf16 v[42:45], v[140:143], v[186:189], v[42:45]
	v_mfma_f32_16x16x32_bf16 v[38:41], v[154:157], v[186:189], v[38:41]
	v_mfma_f32_16x16x32_bf16 v[26:29], v[140:143], v[194:197], v[26:29]
	v_mfma_f32_16x16x32_bf16 v[22:25], v[154:157], v[194:197], v[22:25]
	v_mfma_f32_16x16x32_bf16 v[10:13], v[140:143], v[202:205], v[10:13]
	v_mfma_f32_16x16x32_bf16 v[6:9], v[154:157], v[202:205], v[6:9]
	v_mfma_f32_16x16x32_bf16 v[58:61], v[150:153], v[182:185], v[58:61]
	v_mfma_f32_16x16x32_bf16 v[54:57], v[158:161], v[182:185], v[54:57]
	v_mfma_f32_16x16x32_bf16 v[42:45], v[150:153], v[190:193], v[42:45]
	v_mfma_f32_16x16x32_bf16 v[38:41], v[158:161], v[190:193], v[38:41]
	v_mfma_f32_16x16x32_bf16 v[26:29], v[150:153], v[198:201], v[26:29]
	v_mfma_f32_16x16x32_bf16 v[22:25], v[158:161], v[198:201], v[22:25]
	v_mfma_f32_16x16x32_bf16 v[10:13], v[150:153], v[206:209], v[10:13]
	v_mfma_f32_16x16x32_bf16 v[6:9], v[158:161], v[206:209], v[6:9]
	s_setprio 0
	s_setprio 1
	v_mfma_f32_16x16x32_bf16 v[62:65], v[162:165], v[178:181], v[62:65]
	v_mfma_f32_16x16x32_bf16 v[50:53], v[170:173], v[178:181], v[50:53]
	v_mfma_f32_16x16x32_bf16 v[46:49], v[162:165], v[186:189], v[46:49]
	v_mfma_f32_16x16x32_bf16 v[34:37], v[170:173], v[186:189], v[34:37]
	v_mfma_f32_16x16x32_bf16 v[30:33], v[162:165], v[194:197], v[30:33]
	v_mfma_f32_16x16x32_bf16 v[18:21], v[170:173], v[194:197], v[18:21]
	v_mfma_f32_16x16x32_bf16 v[14:17], v[162:165], v[202:205], v[14:17]
	v_mfma_f32_16x16x32_bf16 v[2:5], v[170:173], v[202:205], v[2:5]
	v_mfma_f32_16x16x32_bf16 v[62:65], v[166:169], v[182:185], v[62:65]
	v_mfma_f32_16x16x32_bf16 v[50:53], v[174:177], v[182:185], v[50:53]
	v_mfma_f32_16x16x32_bf16 v[46:49], v[166:169], v[190:193], v[46:49]
	v_mfma_f32_16x16x32_bf16 v[34:37], v[174:177], v[190:193], v[34:37]
	v_mfma_f32_16x16x32_bf16 v[30:33], v[166:169], v[198:201], v[30:33]
	v_mfma_f32_16x16x32_bf16 v[18:21], v[174:177], v[198:201], v[18:21]
	v_mfma_f32_16x16x32_bf16 v[14:17], v[166:169], v[206:209], v[14:17]
	v_mfma_f32_16x16x32_bf16 v[2:5], v[174:177], v[206:209], v[2:5]
	s_setprio 0
	s_barrier
	s_add_i32 s69, 0, 0x18000
	s_add_i32 s70, 0, 0x1c000
	v_add_u32_e32 v158, s69, v144
	v_add_u32_e32 v174, s70, v144
	ds_read_b128 v[140:143], v158
	ds_read_b128 v[150:153], v158 offset:1024
	ds_read_b128 v[154:157], v158 offset:2048
	ds_read_b128 v[158:161], v158 offset:3072
	ds_read_b128 v[162:165], v174
	ds_read_b128 v[166:169], v174 offset:1024
	ds_read_b128 v[170:173], v174 offset:2048
	ds_read_b128 v[174:177], v174 offset:3072
	s_add_u32 s40, s40, 0x40000
	s_addc_u32 s41, s41, 0
	s_mov_b32 m0, s47
	v_lshl_add_u64 v[218:219], s[40:41], 0, v[132:133]
	ds_read_b128 v[178:181], v148 offset:32768
	ds_read_b128 v[182:185], v148 offset:33792
	ds_read_b128 v[186:189], v148 offset:34816
	ds_read_b128 v[190:193], v148 offset:35840
	ds_read_b128 v[194:197], v148 offset:36864
	ds_read_b128 v[198:201], v148 offset:37888
	ds_read_b128 v[202:205], v148 offset:38912
	ds_read_b128 v[206:209], v148 offset:39936
	global_load_lds_dwordx4 v[218:219], off
	v_lshl_add_u64 v[218:219], s[40:41], 0, v[130:131]
	s_mov_b32 m0, s56
	s_nop 0
	global_load_lds_dwordx4 v[218:219], off
	s_waitcnt vmcnt(8)
	s_waitcnt lgkmcnt(0)
	s_barrier
	s_setprio 1
	s_waitcnt lgkmcnt(0)
	v_mfma_f32_16x16x32_bf16 v[118:121], v[140:143], v[178:181], v[118:121]
	v_mfma_f32_16x16x32_bf16 v[114:117], v[154:157], v[178:181], v[114:117]
	v_mfma_f32_16x16x32_bf16 v[106:109], v[140:143], v[186:189], v[106:109]
	v_mfma_f32_16x16x32_bf16 v[98:101], v[154:157], v[186:189], v[98:101]
	v_mfma_f32_16x16x32_bf16 v[90:93], v[140:143], v[194:197], v[90:93]
	v_mfma_f32_16x16x32_bf16 v[82:85], v[154:157], v[194:197], v[82:85]
	v_mfma_f32_16x16x32_bf16 v[74:77], v[140:143], v[202:205], v[74:77]
	v_mfma_f32_16x16x32_bf16 v[70:73], v[154:157], v[202:205], v[70:73]
	v_mfma_f32_16x16x32_bf16 v[118:121], v[150:153], v[182:185], v[118:121]
	v_mfma_f32_16x16x32_bf16 v[114:117], v[158:161], v[182:185], v[114:117]
	v_mfma_f32_16x16x32_bf16 v[106:109], v[150:153], v[190:193], v[106:109]
	v_mfma_f32_16x16x32_bf16 v[98:101], v[158:161], v[190:193], v[98:101]
	v_mfma_f32_16x16x32_bf16 v[90:93], v[150:153], v[198:201], v[90:93]
	v_mfma_f32_16x16x32_bf16 v[82:85], v[158:161], v[198:201], v[82:85]
	v_mfma_f32_16x16x32_bf16 v[74:77], v[150:153], v[206:209], v[74:77]
	v_mfma_f32_16x16x32_bf16 v[70:73], v[158:161], v[206:209], v[70:73]
	s_setprio 0
	s_setprio 1
	v_mfma_f32_16x16x32_bf16 v[126:129], v[162:165], v[178:181], v[126:129]
	v_mfma_f32_16x16x32_bf16 v[122:125], v[170:173], v[178:181], v[122:125]
	v_mfma_f32_16x16x32_bf16 v[110:113], v[162:165], v[186:189], v[110:113]
	v_mfma_f32_16x16x32_bf16 v[102:105], v[170:173], v[186:189], v[102:105]
	v_mfma_f32_16x16x32_bf16 v[94:97], v[162:165], v[194:197], v[94:97]
	v_mfma_f32_16x16x32_bf16 v[86:89], v[170:173], v[194:197], v[86:89]
	v_mfma_f32_16x16x32_bf16 v[78:81], v[162:165], v[202:205], v[78:81]
	v_mfma_f32_16x16x32_bf16 v[66:69], v[170:173], v[202:205], v[66:69]
	v_mfma_f32_16x16x32_bf16 v[126:129], v[166:169], v[182:185], v[126:129]
	v_mfma_f32_16x16x32_bf16 v[122:125], v[174:177], v[182:185], v[122:125]
	v_mfma_f32_16x16x32_bf16 v[110:113], v[166:169], v[190:193], v[110:113]
	v_mfma_f32_16x16x32_bf16 v[102:105], v[174:177], v[190:193], v[102:105]
	v_mfma_f32_16x16x32_bf16 v[94:97], v[166:169], v[198:201], v[94:97]
	v_mfma_f32_16x16x32_bf16 v[86:89], v[174:177], v[198:201], v[86:89]
	v_mfma_f32_16x16x32_bf16 v[78:81], v[166:169], v[206:209], v[78:81]
	v_mfma_f32_16x16x32_bf16 v[66:69], v[174:177], v[206:209], v[66:69]
	s_setprio 0
	s_barrier
; #define PG8_WAIT_V(n) asm volatile("s_waitcnt vmcnt(" #n ")" ::: "memory")
;     __device__ __forceinline__ void operator()(const f32x4 (&acc)[2][2][4][2], const Unit& u, int wr, int wc, int fr, int fq) const {
;         const int row0 = u.pm * BM + wr * 64 + fr, col0 = u.pn * 128 + wc * 32 + 8 * fq;
; #pragma unroll
;         for (int ai = 0; ai < 2; ++ai)
; #pragma unroll
;             for (int m = 0; m < 4; ++m) {
;                 const int row = row0 + ai * HALF + m * 16;
;                 const float r = __builtin_amdgcn_rsqf(rss[row] * (1.f / 1024.f) + NEPS);
; template <class Epi, class Sched, bool ALIGN_EPI = false, bool SP2 = false>
; __device__ __forceinline__ void gemm_phase(PG8_LAS unsigned char* lds, const Gemm g, const Sched& S, const Epi& E) {
;     ...
;             PG8_LDA(At, 1, 1); PG8_STAGE(PG8_SB(1, 0), b3, voffB); PG8_STAGE(PG8_SB(1, 1), b3 + hstep, voffB); PG8_STAGE(PG8_SA(1, 0), a3, voffA);
;             PG8_WAIT_V(8); PG8_WAIT_L(0); PG8_BAR; PG8_MMA(1, 0, At, B0); PG8_MMA(1, 1, At, B1); PG8_BAR; PG8_SCHED;
;             } else {
;             PG8_LDB(B0, 0, 0); PG8_SCHED; PG8_LDA(At, 0, 0); PG8_STAGE(PG8_SA(1, 1), a1 + hstep, voffA);
;             PG8_WAIT_L(8); PG8_BAR; PG8_WAIT_L(0); PG8_MMA(0, 0, At, B0); PG8_BAR; PG8_SCHED;
;             PG8_LDB(B1, 0, 1); PG8_STAGE(PG8_SB(0, 0), b2, voffB);
;             PG8_BAR; PG8_WAIT_L(0); PG8_MMA(0, 1, At, B1); PG8_BAR;
;             PG8_LDA(At, 0, 1); PG8_STAGE(PG8_SA(0, 0), a2, voffA);
;             PG8_BAR; PG8_WAIT_L(0); PG8_MMA(1, 0, At, B0); PG8_BAR; PG8_SCHED;
;             PG8_STAGE(PG8_SB(0, 1), b2 + hstep, voffB);
;             PG8_WAIT_V(6); PG8_BAR; PG8_MMA(1, 1, At, B1); PG8_BAR;
;             PG8_LDB(B0, 1, 0); PG8_SCHED; PG8_LDA(At, 1, 0); PG8_STAGE(PG8_SA(0, 1), a2 + hstep, voffA);
;             PG8_WAIT_L(8); PG8_BAR; PG8_WAIT_L(0); PG8_MMA(0, 0, At, B0); PG8_BAR; PG8_SCHED;
;             PG8_LDB(B1, 1, 1); PG8_STAGE(PG8_SB(1, 0), b3, voffB);
;             PG8_BAR; PG8_WAIT_L(0); PG8_MMA(0, 1, At, B1); PG8_BAR;
;             PG8_LDA(At, 1, 1); PG8_STAGE(PG8_SA(1, 0), a3, voffA);
;             PG8_BAR; PG8_WAIT_L(0); PG8_MMA(1, 0, At, B0); PG8_BAR; PG8_SCHED;
;             PG8_STAGE(PG8_SB(1, 1), b3 + hstep, voffB);
;             PG8_WAIT_V(6); PG8_BAR; PG8_MMA(1, 1, At, B1); PG8_BAR;
;             }
;         }
;         if constexpr (ALIGN_EPI) { if (wr == 0) PG8_BAR; }
	s_add_i32 s40, s69, s43
	v_lshl_add_u64 v[210:211], v[210:211], 0, s[22:23]
	s_mov_b32 m0, s40
	ds_read_b128 v[178:181], v148 offset:49152
	ds_read_b128 v[182:185], v148 offset:50176
	ds_read_b128 v[186:189], v148 offset:51200
	ds_read_b128 v[190:193], v148 offset:52224
	ds_read_b128 v[194:197], v148 offset:53248
	ds_read_b128 v[198:201], v148 offset:54272
	ds_read_b128 v[202:205], v148 offset:55296
	ds_read_b128 v[206:209], v148 offset:56320
	global_load_lds_dwordx4 v[210:211], off
	s_add_i32 m0, s40, 0x2000
	s_add_u32 s38, s38, 0x40080
	v_lshl_add_u64 v[210:211], v[212:213], 0, s[22:23]
	s_addc_u32 s39, s39, 0
	s_add_i32 s40, s70, s43
	global_load_lds_dwordx4 v[210:211], off
	v_lshl_add_u64 v[210:211], s[38:39], 0, v[132:133]
	s_mov_b32 m0, s40
	s_nop 0
	global_load_lds_dwordx4 v[210:211], off
	v_lshl_add_u64 v[210:211], s[38:39], 0, v[130:131]
	s_add_i32 m0, s40, 0x2000
	s_nop 0
	global_load_lds_dwordx4 v[210:211], off
	v_lshl_add_u64 v[210:211], v[214:215], 0, s[22:23]
	s_mov_b32 m0, s57
	s_nop 0
	global_load_lds_dwordx4 v[210:211], off
	v_lshl_add_u64 v[210:211], v[216:217], 0, s[22:23]
	s_mov_b32 m0, s58
	s_nop 0
	global_load_lds_dwordx4 v[210:211], off
	s_waitcnt vmcnt(8)
	s_waitcnt lgkmcnt(0)
	s_barrier
	s_setprio 1
	s_waitcnt lgkmcnt(0)
	v_mfma_f32_16x16x32_bf16 v[58:61], v[140:143], v[178:181], v[58:61]
	v_mfma_f32_16x16x32_bf16 v[54:57], v[154:157], v[178:181], v[54:57]
	v_mfma_f32_16x16x32_bf16 v[42:45], v[140:143], v[186:189], v[42:45]
	v_mfma_f32_16x16x32_bf16 v[38:41], v[154:157], v[186:189], v[38:41]
	v_mfma_f32_16x16x32_bf16 v[26:29], v[140:143], v[194:197], v[26:29]
	v_mfma_f32_16x16x32_bf16 v[22:25], v[154:157], v[194:197], v[22:25]
	v_mfma_f32_16x16x32_bf16 v[10:13], v[140:143], v[202:205], v[10:13]
	v_mfma_f32_16x16x32_bf16 v[6:9], v[154:157], v[202:205], v[6:9]
	v_mfma_f32_16x16x32_bf16 v[58:61], v[150:153], v[182:185], v[58:61]
	v_mfma_f32_16x16x32_bf16 v[54:57], v[158:161], v[182:185], v[54:57]
	v_mfma_f32_16x16x32_bf16 v[42:45], v[150:153], v[190:193], v[42:45]
	v_mfma_f32_16x16x32_bf16 v[38:41], v[158:161], v[190:193], v[38:41]
	v_mfma_f32_16x16x32_bf16 v[26:29], v[150:153], v[198:201], v[26:29]
	v_mfma_f32_16x16x32_bf16 v[22:25], v[158:161], v[198:201], v[22:25]
	v_mfma_f32_16x16x32_bf16 v[10:13], v[150:153], v[206:209], v[10:13]
	v_mfma_f32_16x16x32_bf16 v[6:9], v[158:161], v[206:209], v[6:9]
	s_setprio 0
	s_setprio 1
	v_mfma_f32_16x16x32_bf16 v[62:65], v[162:165], v[178:181], v[62:65]
	v_mfma_f32_16x16x32_bf16 v[50:53], v[170:173], v[178:181], v[50:53]
	v_mfma_f32_16x16x32_bf16 v[46:49], v[162:165], v[186:189], v[46:49]
	v_mfma_f32_16x16x32_bf16 v[34:37], v[170:173], v[186:189], v[34:37]
	v_mfma_f32_16x16x32_bf16 v[30:33], v[162:165], v[194:197], v[30:33]
	v_mfma_f32_16x16x32_bf16 v[18:21], v[170:173], v[194:197], v[18:21]
	v_mfma_f32_16x16x32_bf16 v[14:17], v[162:165], v[202:205], v[14:17]
	v_mfma_f32_16x16x32_bf16 v[2:5], v[170:173], v[202:205], v[2:5]
	v_mfma_f32_16x16x32_bf16 v[62:65], v[166:169], v[182:185], v[62:65]
	v_mfma_f32_16x16x32_bf16 v[50:53], v[174:177], v[182:185], v[50:53]
	v_mfma_f32_16x16x32_bf16 v[46:49], v[166:169], v[190:193], v[46:49]
	v_mfma_f32_16x16x32_bf16 v[34:37], v[174:177], v[190:193], v[34:37]
	v_mfma_f32_16x16x32_bf16 v[30:33], v[166:169], v[198:201], v[30:33]
	v_mfma_f32_16x16x32_bf16 v[18:21], v[174:177], v[198:201], v[18:21]
	v_mfma_f32_16x16x32_bf16 v[14:17], v[166:169], v[206:209], v[14:17]
	v_mfma_f32_16x16x32_bf16 v[2:5], v[174:177], v[206:209], v[2:5]
	s_setprio 0
	s_barrier
	s_add_i32 s68, s68, 2
	s_add_u32 s36, s36, 0x100
	s_addc_u32 s37, s37, 0
	s_add_u32 s66, s66, 0x100
	s_addc_u32 s67, s67, 0
	s_cmp_gt_u32 s68, 13
	s_cbranch_scc0 .LBB0_1489
	v_lshl_add_u32 v140, s62, 8, v1
	v_ashrrev_i32_e32 v141, 31, v140
	v_lshl_add_u64 v[142:143], v[140:141], 2, s[10:11]
	global_load_dword v200, v[142:143], off
	global_load_dword v201, v[142:143], off offset:64
	global_load_dword v202, v[142:143], off offset:128
	global_load_dword v203, v[142:143], off offset:192
	global_load_dword v204, v[142:143], off offset:512
	global_load_dword v205, v[142:143], off offset:576
	global_load_dword v206, v[142:143], off offset:640
	global_load_dword v207, v[142:143], off offset:704
	s_and_b64 vcc, exec, s[24:25]
	s_cbranch_vccz .LBB0_1492
	s_barrier
; __device__ __forceinline__ unsigned cvt_pk_bf16(float lo, float hi) { unsigned r; asm volatile("v_cvt_pk_bf16_f32 %0, %1, %2" : "=v"(r) : "v"(lo), "v"(hi)); return r; }
; __device__ __forceinline__ float silu_f(float x) { return x * sigmoid_f(x); }
;     __device__ __forceinline__ void operator()(const f32x4 (&acc)[2][2][4][2], const Unit& u, int wr, int wc, int fr, int fq) const {
;         const int row0 = u.pm * BM + wr * 64 + fr, col0 = u.pn * 128 + wc * 32 + 8 * fq;
; #pragma unroll
;         for (int ai = 0; ai < 2; ++ai)
; #pragma unroll
;             for (int m = 0; m < 4; ++m) {
;                 const int row = row0 + ai * HALF + m * 16;
;                 const float r = __builtin_amdgcn_rsqf(rss[row] * (1.f / 1024.f) + NEPS);
;                 float o[8];
; #pragma unroll
;                 for (int n = 0; n < 2; ++n)
; #pragma unroll
;                     for (int e = 0; e < 4; ++e) o[4 * n + e] = silu_f(acc[ai][0][m][n][e] * r) * (acc[ai][1][m][n][e] * r);
;                 u32x4 w; w.x = cvt_pk_bf16(o[0], o[1]); w.y = cvt_pk_bf16(o[2], o[3]); w.z = cvt_pk_bf16(o[4], o[5]); w.w = cvt_pk_bf16(o[6], o[7]);
;                 *(u32x4*)(O + (size_t)row * 2816 + col0) = w;
.LBB0_1492:
	v_lshl_or_b32 v150, s63, 7, v145
	v_ashrrev_i32_e32 v151, 31, v150
	v_mov_b32_e32 v154, v124
	v_mov_b32_e32 v155, v116
	v_mov_b32_e32 v116, v125
	v_lshlrev_b64 v[124:125], 1, v[150:151]
	v_mov_b32_e32 v152, v126
	v_mov_b32_e32 v153, v118
	v_mov_b32_e32 v118, v127
	v_mov_b32_e32 v126, v128
	v_mov_b32_e32 v127, v120
	v_mov_b32_e32 v120, v129
	v_mov_b32_e32 v128, v122
	v_mov_b32_e32 v129, v114
	v_mov_b32_e32 v114, v123
	v_or_b32_e32 v158, 16, v140
	v_ashrrev_i32_e32 v159, 31, v158
	v_lshl_add_u64 v[160:161], v[158:159], 2, s[10:11]
	v_readlane_b32 s70, v250, 5
	v_readlane_b32 s71, v250, 6
	s_andn2_b64 vcc, exec, s[4:5]
	s_mov_b64 s[4:5], -1
	v_mov_b64_e32 v[122:123], s[70:71]
	v_mad_i64_i32 v[156:157], s[36:37], v140, s61, v[122:123]
	v_lshl_add_u64 v[156:157], v[156:157], 0, v[124:125]
	s_mov_b32 s68, s72
	s_waitcnt vmcnt(0)
	v_mov_b32_e32 v141, v200
	v_fmamk_f32 v141, v141, 0x3a800000, v149
	v_rsq_f32_e32 v150, v141
	s_nop 0
	v_pk_mul_f32 v[116:117], v[116:117], v[150:151] op_sel_hi:[1,0]
	v_pk_mul_f32 v[152:153], v[152:153], v[150:151] op_sel_hi:[1,0]
	v_pk_mul_f32 v[118:119], v[118:119], v[150:151] op_sel_hi:[1,0]
	v_pk_mul_f32 v[126:127], v[126:127], v[150:151] op_sel_hi:[1,0]
	v_pk_mul_f32 v[120:121], v[120:121], v[150:151] op_sel_hi:[1,0]
	v_pk_mul_f32 v[128:129], v[128:129], v[150:151] op_sel_hi:[1,0]
	v_pk_mul_f32 v[114:115], v[114:115], v[150:151] op_sel_hi:[1,0]
	v_pk_mul_f32 v[154:155], v[154:155], v[150:151] op_sel_hi:[1,0]
	v_mul_f32_e32 v165, 0xbfb8aa3b, v117
	v_mul_f32_e32 v141, 0xbfb8aa3b, v153
	v_mul_f32_e32 v150, 0xbfb8aa3b, v119
	v_mul_f32_e32 v151, 0xbfb8aa3b, v127
	v_mul_f32_e32 v159, 0xbfb8aa3b, v121
	v_mul_f32_e32 v162, 0xbfb8aa3b, v129
	v_mul_f32_e32 v163, 0xbfb8aa3b, v115
	v_mul_f32_e32 v164, 0xbfb8aa3b, v155
	v_exp_f32_e32 v165, v165
	v_exp_f32_e32 v141, v141
	v_exp_f32_e32 v150, v150
	v_exp_f32_e32 v151, v151
	v_exp_f32_e32 v159, v159
	v_exp_f32_e32 v162, v162
	v_exp_f32_e32 v163, v163
	v_exp_f32_e32 v164, v164
	v_add_f32_e32 v165, 1.0, v165
	v_add_f32_e32 v141, 1.0, v141
	v_add_f32_e32 v150, 1.0, v150
	v_add_f32_e32 v151, 1.0, v151
	v_add_f32_e32 v159, 1.0, v159
	v_add_f32_e32 v162, 1.0, v162
	v_add_f32_e32 v163, 1.0, v163
	v_add_f32_e32 v164, 1.0, v164
	v_rcp_f32_e32 v165, v165
	v_rcp_f32_e32 v141, v141
	v_rcp_f32_e32 v150, v150
	v_rcp_f32_e32 v151, v151
	v_rcp_f32_e32 v159, v159
	v_rcp_f32_e32 v162, v162
	v_rcp_f32_e32 v163, v163
	v_rcp_f32_e32 v164, v164
	v_mul_f32_e32 v117, v117, v165
	v_mul_f32_e32 v141, v153, v141
	v_mul_f32_e32 v119, v119, v150
	v_mul_f32_e32 v127, v127, v151
	v_mul_f32_e32 v121, v121, v159
	v_mul_f32_e32 v129, v129, v162
	v_mul_f32_e32 v115, v115, v163
	v_mul_f32_e32 v150, v155, v164
	v_mul_f32_e32 v117, v116, v117
	v_mul_f32_e32 v141, v152, v141
	v_mul_f32_e32 v118, v118, v119
	v_mul_f32_e32 v119, v126, v127
	v_mul_f32_e32 v120, v120, v121
	v_mul_f32_e32 v121, v128, v129
	v_mul_f32_e32 v126, v114, v115
	v_mul_f32_e32 v127, v154, v150
	v_cvt_pk_bf16_f32 v114, v141, v118
	v_cvt_pk_bf16_f32 v115, v119, v120
	v_cvt_pk_bf16_f32 v116, v121, v126
	v_cvt_pk_bf16_f32 v117, v127, v117
	global_store_dwordx4 v[156:157], v[114:117], off
	s_nop 0
	s_nop 0
	v_mov_b32_e32 v115, v106
	v_mov_b32_e32 v106, v111
	v_mov_b32_e32 v111, v108
	v_mov_b32_e32 v108, v113
	v_mov_b32_e32 v113, v98
	v_mov_b32_e32 v98, v103
	v_mov_b32_e32 v103, v100
	v_mov_b32_e32 v100, v105
	v_mov_b32_e32 v114, v110
	v_mov_b32_e32 v110, v112
	v_mov_b32_e32 v112, v102
	v_mov_b32_e32 v102, v104
	v_or_b32_e32 v104, 32, v140
	v_mad_i64_i32 v[116:117], s[36:37], v158, s61, v[122:123]
	v_lshl_add_u64 v[116:117], v[116:117], 0, v[124:125]
	s_waitcnt vmcnt(7)
	v_mov_b32_e32 v118, v201
	v_fmamk_f32 v105, v118, 0x3a800000, v149
	v_rsq_f32_e32 v118, v105
	v_ashrrev_i32_e32 v105, 31, v104
	v_lshl_add_u64 v[120:121], v[104:105], 2, s[10:11]
	v_pk_mul_f32 v[100:101], v[100:101], v[118:119] op_sel_hi:[1,0]
	v_pk_mul_f32 v[114:115], v[114:115], v[118:119] op_sel_hi:[1,0]
	v_pk_mul_f32 v[106:107], v[106:107], v[118:119] op_sel_hi:[1,0]
	v_pk_mul_f32 v[110:111], v[110:111], v[118:119] op_sel_hi:[1,0]
	v_pk_mul_f32 v[108:109], v[108:109], v[118:119] op_sel_hi:[1,0]
	v_pk_mul_f32 v[112:113], v[112:113], v[118:119] op_sel_hi:[1,0]
	v_pk_mul_f32 v[98:99], v[98:99], v[118:119] op_sel_hi:[1,0]
	v_pk_mul_f32 v[102:103], v[102:103], v[118:119] op_sel_hi:[1,0]
	v_mul_f32_e32 v141, 0xbfb8aa3b, v101
	v_mul_f32_e32 v105, 0xbfb8aa3b, v115
	v_mul_f32_e32 v118, 0xbfb8aa3b, v107
	v_mul_f32_e32 v119, 0xbfb8aa3b, v111
	v_mul_f32_e32 v126, 0xbfb8aa3b, v109
	v_mul_f32_e32 v127, 0xbfb8aa3b, v113
	v_mul_f32_e32 v128, 0xbfb8aa3b, v99
	v_mul_f32_e32 v129, 0xbfb8aa3b, v103
	v_exp_f32_e32 v141, v141
	v_exp_f32_e32 v105, v105
	v_exp_f32_e32 v118, v118
	v_exp_f32_e32 v119, v119
	v_exp_f32_e32 v126, v126
	v_exp_f32_e32 v127, v127
	v_exp_f32_e32 v128, v128
	v_exp_f32_e32 v129, v129
	v_add_f32_e32 v141, 1.0, v141
	v_add_f32_e32 v105, 1.0, v105
	v_add_f32_e32 v118, 1.0, v118
	v_add_f32_e32 v119, 1.0, v119
	v_add_f32_e32 v126, 1.0, v126
	v_add_f32_e32 v127, 1.0, v127
	v_add_f32_e32 v128, 1.0, v128
	v_add_f32_e32 v129, 1.0, v129
	v_rcp_f32_e32 v141, v141
	v_rcp_f32_e32 v105, v105
	v_rcp_f32_e32 v118, v118
	v_rcp_f32_e32 v119, v119
	v_rcp_f32_e32 v126, v126
	v_rcp_f32_e32 v127, v127
	v_rcp_f32_e32 v128, v128
	v_rcp_f32_e32 v129, v129
	v_mul_f32_e32 v101, v101, v141
	v_mul_f32_e32 v105, v115, v105
	v_mul_f32_e32 v107, v107, v118
	v_mul_f32_e32 v111, v111, v119
	v_mul_f32_e32 v109, v109, v126
	v_mul_f32_e32 v113, v113, v127
	v_mul_f32_e32 v99, v99, v128
	v_mul_f32_e32 v103, v103, v129
	v_mul_f32_e32 v101, v100, v101
	v_mul_f32_e32 v105, v114, v105
	v_mul_f32_e32 v106, v106, v107
	v_mul_f32_e32 v107, v110, v111
	v_mul_f32_e32 v108, v108, v109
	v_mul_f32_e32 v109, v112, v113
	v_mul_f32_e32 v110, v98, v99
	v_mul_f32_e32 v102, v102, v103
	v_cvt_pk_bf16_f32 v98, v105, v106
	v_cvt_pk_bf16_f32 v99, v107, v108
	v_cvt_pk_bf16_f32 v100, v109, v110
	v_cvt_pk_bf16_f32 v101, v102, v101
	global_store_dwordx4 v[116:117], v[98:101], off
	s_nop 0
	s_nop 0
	v_mov_b32_e32 v99, v90
	v_mov_b32_e32 v90, v95
	v_mov_b32_e32 v95, v92
	v_mov_b32_e32 v92, v97
	v_mov_b32_e32 v97, v82
	v_mov_b32_e32 v82, v87
	v_mov_b32_e32 v87, v84
	v_mov_b32_e32 v84, v89
	v_mov_b32_e32 v98, v94
	v_mov_b32_e32 v94, v96
	v_mov_b32_e32 v96, v86
	v_mov_b32_e32 v86, v88
	v_or_b32_e32 v88, 48, v140
	v_mad_i64_i32 v[100:101], s[36:37], v104, s61, v[122:123]
	v_lshl_add_u64 v[100:101], v[100:101], 0, v[124:125]
	s_waitcnt vmcnt(7)
; __device__ __forceinline__ unsigned cvt_pk_bf16(float lo, float hi) { unsigned r; asm volatile("v_cvt_pk_bf16_f32 %0, %1, %2" : "=v"(r) : "v"(lo), "v"(hi)); return r; }
; __device__ __forceinline__ float silu_f(float x) { return x * sigmoid_f(x); }
;     __device__ __forceinline__ void operator()(const f32x4 (&acc)[2][2][4][2], const Unit& u, int wr, int wc, int fr, int fq) const {
;         const int row0 = u.pm * BM + wr * 64 + fr, col0 = u.pn * 128 + wc * 32 + 8 * fq;
; #pragma unroll
;         for (int ai = 0; ai < 2; ++ai)
; #pragma unroll
;             for (int m = 0; m < 4; ++m) {
;                 const int row = row0 + ai * HALF + m * 16;
;                 const float r = __builtin_amdgcn_rsqf(rss[row] * (1.f / 1024.f) + NEPS);
;                 float o[8];
; #pragma unroll
;                 for (int n = 0; n < 2; ++n)
; #pragma unroll
;                     for (int e = 0; e < 4; ++e) o[4 * n + e] = silu_f(acc[ai][0][m][n][e] * r) * (acc[ai][1][m][n][e] * r);
;                 u32x4 w; w.x = cvt_pk_bf16(o[0], o[1]); w.y = cvt_pk_bf16(o[2], o[3]); w.z = cvt_pk_bf16(o[4], o[5]); w.w = cvt_pk_bf16(o[6], o[7]);
;                 *(u32x4*)(O + (size_t)row * 2816 + col0) = w;
	v_mov_b32_e32 v102, v202
	v_fmamk_f32 v89, v102, 0x3a800000, v149
	v_rsq_f32_e32 v102, v89
	v_ashrrev_i32_e32 v89, 31, v88
	v_lshl_add_u64 v[104:105], v[88:89], 2, s[10:11]
	v_pk_mul_f32 v[84:85], v[84:85], v[102:103] op_sel_hi:[1,0]
	v_pk_mul_f32 v[98:99], v[98:99], v[102:103] op_sel_hi:[1,0]
	v_pk_mul_f32 v[90:91], v[90:91], v[102:103] op_sel_hi:[1,0]
	v_pk_mul_f32 v[94:95], v[94:95], v[102:103] op_sel_hi:[1,0]
	v_pk_mul_f32 v[92:93], v[92:93], v[102:103] op_sel_hi:[1,0]
	v_pk_mul_f32 v[96:97], v[96:97], v[102:103] op_sel_hi:[1,0]
	v_pk_mul_f32 v[82:83], v[82:83], v[102:103] op_sel_hi:[1,0]
	v_pk_mul_f32 v[86:87], v[86:87], v[102:103] op_sel_hi:[1,0]
	v_mul_f32_e32 v110, 0xbfb8aa3b, v85
	v_mul_f32_e32 v89, 0xbfb8aa3b, v99
	v_mul_f32_e32 v102, 0xbfb8aa3b, v91
	v_mul_f32_e32 v103, 0xbfb8aa3b, v95
	v_mul_f32_e32 v106, 0xbfb8aa3b, v93
	v_mul_f32_e32 v107, 0xbfb8aa3b, v97
	v_mul_f32_e32 v108, 0xbfb8aa3b, v83
	v_mul_f32_e32 v109, 0xbfb8aa3b, v87
	v_exp_f32_e32 v110, v110
	v_exp_f32_e32 v89, v89
	v_exp_f32_e32 v102, v102
	v_exp_f32_e32 v103, v103
	v_exp_f32_e32 v106, v106
	v_exp_f32_e32 v107, v107
	v_exp_f32_e32 v108, v108
	v_exp_f32_e32 v109, v109
	v_add_f32_e32 v110, 1.0, v110
	v_add_f32_e32 v89, 1.0, v89
	v_add_f32_e32 v102, 1.0, v102
	v_add_f32_e32 v103, 1.0, v103
	v_add_f32_e32 v106, 1.0, v106
	v_add_f32_e32 v107, 1.0, v107
	v_add_f32_e32 v108, 1.0, v108
	v_add_f32_e32 v109, 1.0, v109
	v_rcp_f32_e32 v110, v110
	v_rcp_f32_e32 v89, v89
	v_rcp_f32_e32 v102, v102
	v_rcp_f32_e32 v103, v103
	v_rcp_f32_e32 v106, v106
	v_rcp_f32_e32 v107, v107
	v_rcp_f32_e32 v108, v108
	v_rcp_f32_e32 v109, v109
	v_mul_f32_e32 v85, v85, v110
	v_mul_f32_e32 v89, v99, v89
	v_mul_f32_e32 v91, v91, v102
	v_mul_f32_e32 v95, v95, v103
	v_mul_f32_e32 v93, v93, v106
	v_mul_f32_e32 v97, v97, v107
	v_mul_f32_e32 v83, v83, v108
	v_mul_f32_e32 v87, v87, v109
	v_mul_f32_e32 v85, v84, v85
	v_mul_f32_e32 v89, v98, v89
	v_mul_f32_e32 v90, v90, v91
	v_mul_f32_e32 v91, v94, v95
	v_mul_f32_e32 v92, v92, v93
	v_mul_f32_e32 v93, v96, v97
	v_mul_f32_e32 v94, v82, v83
	v_mul_f32_e32 v86, v86, v87
	v_cvt_pk_bf16_f32 v82, v89, v90
	v_cvt_pk_bf16_f32 v83, v91, v92
	v_cvt_pk_bf16_f32 v84, v93, v94
	v_cvt_pk_bf16_f32 v85, v86, v85
	global_store_dwordx4 v[100:101], v[82:85], off
	s_nop 0
	s_nop 0
	v_mov_b32_e32 v82, v78
	v_mov_b32_e32 v78, v80
	v_mov_b32_e32 v80, v66
	v_mov_b32_e32 v66, v68
	v_mov_b32_e32 v83, v74
	v_mov_b32_e32 v74, v79
	v_mov_b32_e32 v79, v76
	v_mov_b32_e32 v76, v81
	v_mov_b32_e32 v81, v70
	v_mov_b32_e32 v70, v67
	v_mov_b32_e32 v67, v72
	v_mov_b32_e32 v72, v69
	s_waitcnt vmcnt(7)
	v_mov_b32_e32 v84, v203
	v_fmamk_f32 v68, v84, 0x3a800000, v149
	v_rsq_f32_e32 v68, v68
	v_mad_i64_i32 v[84:85], s[36:37], v88, s61, v[122:123]
	v_lshl_add_u64 v[84:85], v[84:85], 0, v[124:125]
	v_pk_mul_f32 v[82:83], v[82:83], v[68:69] op_sel_hi:[1,0]
	v_pk_mul_f32 v[74:75], v[74:75], v[68:69] op_sel_hi:[1,0]
	v_pk_mul_f32 v[78:79], v[78:79], v[68:69] op_sel_hi:[1,0]
	v_pk_mul_f32 v[76:77], v[76:77], v[68:69] op_sel_hi:[1,0]
	v_pk_mul_f32 v[80:81], v[80:81], v[68:69] op_sel_hi:[1,0]
	v_pk_mul_f32 v[70:71], v[70:71], v[68:69] op_sel_hi:[1,0]
	v_pk_mul_f32 v[66:67], v[66:67], v[68:69] op_sel_hi:[1,0]
	v_pk_mul_f32 v[68:69], v[72:73], v[68:69] op_sel_hi:[1,0]
	v_mul_f32_e32 v72, 0xbfb8aa3b, v83
	v_mul_f32_e32 v91, 0xbfb8aa3b, v69
	v_mul_f32_e32 v73, 0xbfb8aa3b, v75
	v_mul_f32_e32 v86, 0xbfb8aa3b, v79
	v_mul_f32_e32 v87, 0xbfb8aa3b, v77
	v_mul_f32_e32 v88, 0xbfb8aa3b, v81
	v_mul_f32_e32 v89, 0xbfb8aa3b, v71
	v_mul_f32_e32 v90, 0xbfb8aa3b, v67
	v_exp_f32_e32 v91, v91
	v_exp_f32_e32 v72, v72
	v_exp_f32_e32 v73, v73
	v_exp_f32_e32 v86, v86
	v_exp_f32_e32 v87, v87
	v_exp_f32_e32 v88, v88
	v_exp_f32_e32 v89, v89
	v_exp_f32_e32 v90, v90
	v_add_f32_e32 v91, 1.0, v91
	v_add_f32_e32 v72, 1.0, v72
	v_add_f32_e32 v73, 1.0, v73
	v_add_f32_e32 v86, 1.0, v86
	v_add_f32_e32 v87, 1.0, v87
	v_add_f32_e32 v88, 1.0, v88
	v_add_f32_e32 v89, 1.0, v89
	v_add_f32_e32 v90, 1.0, v90
	v_rcp_f32_e32 v91, v91
	v_rcp_f32_e32 v72, v72
	v_rcp_f32_e32 v73, v73
	v_rcp_f32_e32 v86, v86
	v_rcp_f32_e32 v87, v87
	v_rcp_f32_e32 v88, v88
	v_rcp_f32_e32 v89, v89
	v_rcp_f32_e32 v90, v90
	v_mul_f32_e32 v69, v69, v91
	v_mul_f32_e32 v72, v83, v72
	v_mul_f32_e32 v73, v75, v73
	v_mul_f32_e32 v75, v79, v86
	v_mul_f32_e32 v77, v77, v87
	v_mul_f32_e32 v79, v81, v88
	v_mul_f32_e32 v71, v71, v89
	v_mul_f32_e32 v67, v67, v90
	v_mul_f32_e32 v69, v68, v69
	v_mul_f32_e32 v72, v82, v72
	v_mul_f32_e32 v73, v74, v73
	v_mul_f32_e32 v74, v78, v75
	v_mul_f32_e32 v75, v76, v77
	v_mul_f32_e32 v76, v80, v79
	v_mul_f32_e32 v70, v70, v71
	v_mul_f32_e32 v71, v66, v67
	v_cvt_pk_bf16_f32 v66, v72, v73
	v_cvt_pk_bf16_f32 v67, v74, v75
	v_cvt_pk_bf16_f32 v68, v76, v70
	v_cvt_pk_bf16_f32 v69, v71, v69
	global_store_dwordx4 v[84:85], v[66:69], off
	s_nop 0
	s_nop 0
	v_mov_b32_e32 v66, v62
	v_mov_b32_e32 v62, v64
	v_mov_b32_e32 v64, v50
	v_mov_b32_e32 v50, v52
	v_mov_b32_e32 v67, v58
	v_mov_b32_e32 v58, v63
	v_mov_b32_e32 v63, v60
	v_mov_b32_e32 v60, v65
	v_mov_b32_e32 v65, v54
	v_mov_b32_e32 v54, v51
	v_mov_b32_e32 v51, v56
	v_mov_b32_e32 v56, v53
	v_add_u32_e32 v53, 0x80, v140
	s_waitcnt vmcnt(7)
; __device__ __forceinline__ unsigned cvt_pk_bf16(float lo, float hi) { unsigned r; asm volatile("v_cvt_pk_bf16_f32 %0, %1, %2" : "=v"(r) : "v"(lo), "v"(hi)); return r; }
; __device__ __forceinline__ float silu_f(float x) { return x * sigmoid_f(x); }
;     __device__ __forceinline__ void operator()(const f32x4 (&acc)[2][2][4][2], const Unit& u, int wr, int wc, int fr, int fq) const {
;         const int row0 = u.pm * BM + wr * 64 + fr, col0 = u.pn * 128 + wc * 32 + 8 * fq;
; #pragma unroll
;         for (int ai = 0; ai < 2; ++ai)
; #pragma unroll
;             for (int m = 0; m < 4; ++m) {
;                 const int row = row0 + ai * HALF + m * 16;
;                 const float r = __builtin_amdgcn_rsqf(rss[row] * (1.f / 1024.f) + NEPS);
;                 float o[8];
; #pragma unroll
;                 for (int n = 0; n < 2; ++n)
; #pragma unroll
;                     for (int e = 0; e < 4; ++e) o[4 * n + e] = silu_f(acc[ai][0][m][n][e] * r) * (acc[ai][1][m][n][e] * r);
;                 u32x4 w; w.x = cvt_pk_bf16(o[0], o[1]); w.y = cvt_pk_bf16(o[2], o[3]); w.z = cvt_pk_bf16(o[4], o[5]); w.w = cvt_pk_bf16(o[6], o[7]);
;                 *(u32x4*)(O + (size_t)row * 2816 + col0) = w;
	v_mov_b32_e32 v68, v204
	v_fmamk_f32 v52, v68, 0x3a800000, v149
	v_rsq_f32_e32 v52, v52
	v_mad_i64_i32 v[68:69], s[36:37], v53, s61, v[122:123]
	v_lshl_add_u64 v[68:69], v[68:69], 0, v[124:125]
	v_pk_mul_f32 v[66:67], v[66:67], v[52:53] op_sel_hi:[1,0]
	v_pk_mul_f32 v[58:59], v[58:59], v[52:53] op_sel_hi:[1,0]
	v_pk_mul_f32 v[62:63], v[62:63], v[52:53] op_sel_hi:[1,0]
	v_pk_mul_f32 v[60:61], v[60:61], v[52:53] op_sel_hi:[1,0]
	v_pk_mul_f32 v[64:65], v[64:65], v[52:53] op_sel_hi:[1,0]
	v_pk_mul_f32 v[54:55], v[54:55], v[52:53] op_sel_hi:[1,0]
	v_pk_mul_f32 v[50:51], v[50:51], v[52:53] op_sel_hi:[1,0]
	v_pk_mul_f32 v[52:53], v[56:57], v[52:53] op_sel_hi:[1,0]
	v_mul_f32_e32 v56, 0xbfb8aa3b, v67
	v_mul_f32_e32 v75, 0xbfb8aa3b, v53
	v_mul_f32_e32 v57, 0xbfb8aa3b, v59
	v_mul_f32_e32 v70, 0xbfb8aa3b, v63
	v_mul_f32_e32 v71, 0xbfb8aa3b, v61
	v_mul_f32_e32 v72, 0xbfb8aa3b, v65
	v_mul_f32_e32 v73, 0xbfb8aa3b, v55
	v_mul_f32_e32 v74, 0xbfb8aa3b, v51
	v_exp_f32_e32 v75, v75
	v_exp_f32_e32 v56, v56
	v_exp_f32_e32 v57, v57
	v_exp_f32_e32 v70, v70
	v_exp_f32_e32 v71, v71
	v_exp_f32_e32 v72, v72
	v_exp_f32_e32 v73, v73
	v_exp_f32_e32 v74, v74
	v_add_f32_e32 v75, 1.0, v75
	v_add_f32_e32 v56, 1.0, v56
	v_add_f32_e32 v57, 1.0, v57
	v_add_f32_e32 v70, 1.0, v70
	v_add_f32_e32 v71, 1.0, v71
	v_add_f32_e32 v72, 1.0, v72
	v_add_f32_e32 v73, 1.0, v73
	v_add_f32_e32 v74, 1.0, v74
	v_rcp_f32_e32 v75, v75
	v_rcp_f32_e32 v56, v56
	v_rcp_f32_e32 v57, v57
	v_rcp_f32_e32 v70, v70
	v_rcp_f32_e32 v71, v71
	v_rcp_f32_e32 v72, v72
	v_rcp_f32_e32 v73, v73
	v_rcp_f32_e32 v74, v74
	v_mul_f32_e32 v53, v53, v75
	v_mul_f32_e32 v56, v67, v56
	v_mul_f32_e32 v57, v59, v57
	v_mul_f32_e32 v59, v63, v70
	v_mul_f32_e32 v61, v61, v71
	v_mul_f32_e32 v63, v65, v72
	v_mul_f32_e32 v55, v55, v73
	v_mul_f32_e32 v51, v51, v74
	v_mul_f32_e32 v53, v52, v53
	v_mul_f32_e32 v56, v66, v56
	v_mul_f32_e32 v57, v58, v57
	v_mul_f32_e32 v58, v62, v59
	v_mul_f32_e32 v59, v60, v61
	v_mul_f32_e32 v60, v64, v63
	v_mul_f32_e32 v54, v54, v55
	v_mul_f32_e32 v55, v50, v51
	v_cvt_pk_bf16_f32 v50, v56, v57
	v_cvt_pk_bf16_f32 v51, v58, v59
	v_cvt_pk_bf16_f32 v52, v60, v54
	v_cvt_pk_bf16_f32 v53, v55, v53
	global_store_dwordx4 v[68:69], v[50:53], off
	s_nop 0
	s_nop 0
	v_mov_b32_e32 v50, v46
	v_mov_b32_e32 v46, v48
	v_mov_b32_e32 v48, v34
	v_mov_b32_e32 v34, v36
	v_mov_b32_e32 v51, v42
	v_mov_b32_e32 v42, v47
	v_mov_b32_e32 v47, v44
	v_mov_b32_e32 v44, v49
	v_mov_b32_e32 v49, v38
	v_mov_b32_e32 v38, v35
	v_mov_b32_e32 v35, v40
	v_mov_b32_e32 v40, v37
	v_add_u32_e32 v37, 0x90, v140
	s_waitcnt vmcnt(7)
	v_mov_b32_e32 v52, v205
	v_fmamk_f32 v36, v52, 0x3a800000, v149
	v_rsq_f32_e32 v36, v36
	v_mad_i64_i32 v[52:53], s[36:37], v37, s61, v[122:123]
	v_lshl_add_u64 v[52:53], v[52:53], 0, v[124:125]
	v_pk_mul_f32 v[50:51], v[50:51], v[36:37] op_sel_hi:[1,0]
	v_pk_mul_f32 v[42:43], v[42:43], v[36:37] op_sel_hi:[1,0]
	v_pk_mul_f32 v[46:47], v[46:47], v[36:37] op_sel_hi:[1,0]
	v_pk_mul_f32 v[44:45], v[44:45], v[36:37] op_sel_hi:[1,0]
	v_pk_mul_f32 v[48:49], v[48:49], v[36:37] op_sel_hi:[1,0]
	v_pk_mul_f32 v[38:39], v[38:39], v[36:37] op_sel_hi:[1,0]
	v_pk_mul_f32 v[34:35], v[34:35], v[36:37] op_sel_hi:[1,0]
	v_pk_mul_f32 v[36:37], v[40:41], v[36:37] op_sel_hi:[1,0]
	v_mul_f32_e32 v40, 0xbfb8aa3b, v51
	v_mul_f32_e32 v59, 0xbfb8aa3b, v37
	v_mul_f32_e32 v41, 0xbfb8aa3b, v43
	v_mul_f32_e32 v54, 0xbfb8aa3b, v47
	v_mul_f32_e32 v55, 0xbfb8aa3b, v45
	v_mul_f32_e32 v56, 0xbfb8aa3b, v49
	v_mul_f32_e32 v57, 0xbfb8aa3b, v39
	v_mul_f32_e32 v58, 0xbfb8aa3b, v35
	v_exp_f32_e32 v59, v59
	v_exp_f32_e32 v40, v40
	v_exp_f32_e32 v41, v41
	v_exp_f32_e32 v54, v54
	v_exp_f32_e32 v55, v55
	v_exp_f32_e32 v56, v56
	v_exp_f32_e32 v57, v57
	v_exp_f32_e32 v58, v58
	v_add_f32_e32 v59, 1.0, v59
	v_add_f32_e32 v40, 1.0, v40
	v_add_f32_e32 v41, 1.0, v41
	v_add_f32_e32 v54, 1.0, v54
	v_add_f32_e32 v55, 1.0, v55
	v_add_f32_e32 v56, 1.0, v56
	v_add_f32_e32 v57, 1.0, v57
	v_add_f32_e32 v58, 1.0, v58
	v_rcp_f32_e32 v59, v59
	v_rcp_f32_e32 v40, v40
	v_rcp_f32_e32 v41, v41
	v_rcp_f32_e32 v54, v54
	v_rcp_f32_e32 v55, v55
	v_rcp_f32_e32 v56, v56
	v_rcp_f32_e32 v57, v57
	v_rcp_f32_e32 v58, v58
	v_mul_f32_e32 v37, v37, v59
	v_mul_f32_e32 v40, v51, v40
	v_mul_f32_e32 v41, v43, v41
	v_mul_f32_e32 v43, v47, v54
	v_mul_f32_e32 v45, v45, v55
	v_mul_f32_e32 v47, v49, v56
	v_mul_f32_e32 v39, v39, v57
	v_mul_f32_e32 v35, v35, v58
	v_mul_f32_e32 v37, v36, v37
	v_mul_f32_e32 v40, v50, v40
	v_mul_f32_e32 v41, v42, v41
	v_mul_f32_e32 v42, v46, v43
	v_mul_f32_e32 v43, v44, v45
	v_mul_f32_e32 v44, v48, v47
	v_mul_f32_e32 v38, v38, v39
	v_mul_f32_e32 v39, v34, v35
	v_cvt_pk_bf16_f32 v34, v40, v41
	v_cvt_pk_bf16_f32 v35, v42, v43
	v_cvt_pk_bf16_f32 v36, v44, v38
	v_cvt_pk_bf16_f32 v37, v39, v37
	global_store_dwordx4 v[52:53], v[34:37], off
	s_nop 0
	s_nop 0
	v_mov_b32_e32 v34, v30
	v_mov_b32_e32 v30, v32
	v_mov_b32_e32 v32, v18
	v_mov_b32_e32 v18, v20
	v_mov_b32_e32 v35, v26
	v_mov_b32_e32 v26, v31
	v_mov_b32_e32 v31, v28
	v_mov_b32_e32 v28, v33
	v_mov_b32_e32 v33, v22
	v_mov_b32_e32 v22, v19
	v_mov_b32_e32 v19, v24
	v_mov_b32_e32 v24, v21
	v_add_u32_e32 v21, 0xa0, v140
	s_waitcnt vmcnt(7)
; __device__ __forceinline__ unsigned cvt_pk_bf16(float lo, float hi) { unsigned r; asm volatile("v_cvt_pk_bf16_f32 %0, %1, %2" : "=v"(r) : "v"(lo), "v"(hi)); return r; }
; __device__ __forceinline__ float silu_f(float x) { return x * sigmoid_f(x); }
; #define PG8_BAR __builtin_amdgcn_s_barrier()
;     __device__ __forceinline__ void operator()(const f32x4 (&acc)[2][2][4][2], const Unit& u, int wr, int wc, int fr, int fq) const {
;     ...
;         for (int ai = 0; ai < 2; ++ai)
; #pragma unroll
;             for (int m = 0; m < 4; ++m) {
;                 const int row = row0 + ai * HALF + m * 16;
;                 const float r = __builtin_amdgcn_rsqf(rss[row] * (1.f / 1024.f) + NEPS);
;                 float o[8];
; #pragma unroll
;                 for (int n = 0; n < 2; ++n)
; #pragma unroll
;                     for (int e = 0; e < 4; ++e) o[4 * n + e] = silu_f(acc[ai][0][m][n][e] * r) * (acc[ai][1][m][n][e] * r);
;                 u32x4 w; w.x = cvt_pk_bf16(o[0], o[1]); w.y = cvt_pk_bf16(o[2], o[3]); w.z = cvt_pk_bf16(o[4], o[5]); w.w = cvt_pk_bf16(o[6], o[7]);
;                 *(u32x4*)(O + (size_t)row * 2816 + col0) = w;
; template <class Epi, class Sched, bool ALIGN_EPI = false, bool SP2 = false>
; __device__ __forceinline__ void gemm_phase(PG8_LAS unsigned char* lds, const Gemm g, const Sched& S, const Epi& E) {
;     ...
;         if (!has_next) break;
; #pragma unroll
;         for (int a = 0; a < 2; ++a)
; #pragma unroll
;             for (int b = 0; b < 2; ++b)
; #pragma unroll
;                 for (int m = 0; m < 4; ++m)
; #pragma unroll
;                     for (int n = 0; n < 2; ++n) acc[a][b][m][n] = (f32x4){0.f, 0.f, 0.f, 0.f};
;         cur = nxt; cA = nA; cB = nB; ++ui;
;         if constexpr (ALIGN_EPI) { if (wr == 1) PG8_BAR; }
	v_mov_b32_e32 v36, v206
	v_fmamk_f32 v20, v36, 0x3a800000, v149
	v_rsq_f32_e32 v20, v20
	v_mad_i64_i32 v[36:37], s[36:37], v21, s61, v[122:123]
	v_lshl_add_u64 v[36:37], v[36:37], 0, v[124:125]
	v_pk_mul_f32 v[34:35], v[34:35], v[20:21] op_sel_hi:[1,0]
	v_pk_mul_f32 v[26:27], v[26:27], v[20:21] op_sel_hi:[1,0]
	v_pk_mul_f32 v[30:31], v[30:31], v[20:21] op_sel_hi:[1,0]
	v_pk_mul_f32 v[28:29], v[28:29], v[20:21] op_sel_hi:[1,0]
	v_pk_mul_f32 v[32:33], v[32:33], v[20:21] op_sel_hi:[1,0]
	v_pk_mul_f32 v[22:23], v[22:23], v[20:21] op_sel_hi:[1,0]
	v_pk_mul_f32 v[18:19], v[18:19], v[20:21] op_sel_hi:[1,0]
	v_pk_mul_f32 v[20:21], v[24:25], v[20:21] op_sel_hi:[1,0]
	v_mul_f32_e32 v24, 0xbfb8aa3b, v35
	v_mul_f32_e32 v43, 0xbfb8aa3b, v21
	v_mul_f32_e32 v25, 0xbfb8aa3b, v27
	v_mul_f32_e32 v38, 0xbfb8aa3b, v31
	v_mul_f32_e32 v39, 0xbfb8aa3b, v29
	v_mul_f32_e32 v40, 0xbfb8aa3b, v33
	v_mul_f32_e32 v41, 0xbfb8aa3b, v23
	v_mul_f32_e32 v42, 0xbfb8aa3b, v19
	v_exp_f32_e32 v43, v43
	v_exp_f32_e32 v24, v24
	v_exp_f32_e32 v25, v25
	v_exp_f32_e32 v38, v38
	v_exp_f32_e32 v39, v39
	v_exp_f32_e32 v40, v40
	v_exp_f32_e32 v41, v41
	v_exp_f32_e32 v42, v42
	v_add_f32_e32 v43, 1.0, v43
	v_add_f32_e32 v24, 1.0, v24
	v_add_f32_e32 v25, 1.0, v25
	v_add_f32_e32 v38, 1.0, v38
	v_add_f32_e32 v39, 1.0, v39
	v_add_f32_e32 v40, 1.0, v40
	v_add_f32_e32 v41, 1.0, v41
	v_add_f32_e32 v42, 1.0, v42
	v_rcp_f32_e32 v43, v43
	v_rcp_f32_e32 v24, v24
	v_rcp_f32_e32 v25, v25
	v_rcp_f32_e32 v38, v38
	v_rcp_f32_e32 v39, v39
	v_rcp_f32_e32 v40, v40
	v_rcp_f32_e32 v41, v41
	v_rcp_f32_e32 v42, v42
	v_mul_f32_e32 v21, v21, v43
	v_mul_f32_e32 v24, v35, v24
	v_mul_f32_e32 v25, v27, v25
	v_mul_f32_e32 v27, v31, v38
	v_mul_f32_e32 v29, v29, v39
	v_mul_f32_e32 v31, v33, v40
	v_mul_f32_e32 v23, v23, v41
	v_mul_f32_e32 v19, v19, v42
	v_mul_f32_e32 v21, v20, v21
	v_mul_f32_e32 v24, v34, v24
	v_mul_f32_e32 v25, v26, v25
	v_mul_f32_e32 v26, v30, v27
	v_mul_f32_e32 v27, v28, v29
	v_mul_f32_e32 v28, v32, v31
	v_mul_f32_e32 v22, v22, v23
	v_mul_f32_e32 v23, v18, v19
	v_cvt_pk_bf16_f32 v18, v24, v25
	v_cvt_pk_bf16_f32 v19, v26, v27
	v_cvt_pk_bf16_f32 v20, v28, v22
	v_cvt_pk_bf16_f32 v21, v23, v21
	global_store_dwordx4 v[36:37], v[18:21], off
	s_nop 0
	s_nop 0
	v_mov_b32_e32 v18, v14
	v_mov_b32_e32 v14, v16
	v_mov_b32_e32 v16, v2
	v_mov_b32_e32 v2, v4
	v_mov_b32_e32 v19, v10
	v_mov_b32_e32 v10, v15
	v_mov_b32_e32 v15, v12
	v_mov_b32_e32 v12, v17
	v_mov_b32_e32 v17, v6
	v_mov_b32_e32 v6, v3
	v_mov_b32_e32 v3, v8
	v_mov_b32_e32 v8, v5
	v_add_u32_e32 v5, 0xb0, v140
	s_waitcnt vmcnt(7)
	v_mov_b32_e32 v20, v207
	v_fmamk_f32 v4, v20, 0x3a800000, v149
	v_rsq_f32_e32 v4, v4
	v_mad_i64_i32 v[20:21], s[36:37], v5, s61, v[122:123]
	v_lshl_add_u64 v[20:21], v[20:21], 0, v[124:125]
	v_pk_mul_f32 v[18:19], v[18:19], v[4:5] op_sel_hi:[1,0]
	v_pk_mul_f32 v[10:11], v[10:11], v[4:5] op_sel_hi:[1,0]
	v_pk_mul_f32 v[14:15], v[14:15], v[4:5] op_sel_hi:[1,0]
	v_pk_mul_f32 v[12:13], v[12:13], v[4:5] op_sel_hi:[1,0]
	v_pk_mul_f32 v[16:17], v[16:17], v[4:5] op_sel_hi:[1,0]
	v_pk_mul_f32 v[6:7], v[6:7], v[4:5] op_sel_hi:[1,0]
	v_pk_mul_f32 v[2:3], v[2:3], v[4:5] op_sel_hi:[1,0]
	v_pk_mul_f32 v[4:5], v[8:9], v[4:5] op_sel_hi:[1,0]
	v_mul_f32_e32 v8, 0xbfb8aa3b, v19
	v_mul_f32_e32 v27, 0xbfb8aa3b, v5
	v_mul_f32_e32 v9, 0xbfb8aa3b, v11
	v_mul_f32_e32 v22, 0xbfb8aa3b, v15
	v_mul_f32_e32 v23, 0xbfb8aa3b, v13
	v_mul_f32_e32 v24, 0xbfb8aa3b, v17
	v_mul_f32_e32 v25, 0xbfb8aa3b, v7
	v_mul_f32_e32 v26, 0xbfb8aa3b, v3
	v_exp_f32_e32 v27, v27
	v_exp_f32_e32 v8, v8
	v_exp_f32_e32 v9, v9
	v_exp_f32_e32 v22, v22
	v_exp_f32_e32 v23, v23
	v_exp_f32_e32 v24, v24
	v_exp_f32_e32 v25, v25
	v_exp_f32_e32 v26, v26
	v_add_f32_e32 v27, 1.0, v27
	v_add_f32_e32 v8, 1.0, v8
	v_add_f32_e32 v9, 1.0, v9
	v_add_f32_e32 v22, 1.0, v22
	v_add_f32_e32 v23, 1.0, v23
	v_add_f32_e32 v24, 1.0, v24
	v_add_f32_e32 v25, 1.0, v25
	v_add_f32_e32 v26, 1.0, v26
	v_rcp_f32_e32 v27, v27
	v_rcp_f32_e32 v8, v8
	v_rcp_f32_e32 v9, v9
	v_rcp_f32_e32 v22, v22
	v_rcp_f32_e32 v23, v23
	v_rcp_f32_e32 v24, v24
	v_rcp_f32_e32 v25, v25
	v_rcp_f32_e32 v26, v26
	v_mul_f32_e32 v5, v5, v27
	v_mul_f32_e32 v8, v19, v8
	v_mul_f32_e32 v9, v11, v9
	v_mul_f32_e32 v11, v15, v22
	v_mul_f32_e32 v13, v13, v23
	v_mul_f32_e32 v15, v17, v24
	v_mul_f32_e32 v7, v7, v25
	v_mul_f32_e32 v3, v3, v26
	v_mul_f32_e32 v5, v4, v5
	v_mul_f32_e32 v8, v18, v8
	v_mul_f32_e32 v9, v10, v9
	v_mul_f32_e32 v10, v14, v11
	v_mul_f32_e32 v11, v12, v13
	v_mul_f32_e32 v12, v16, v15
	v_mul_f32_e32 v6, v6, v7
	v_mul_f32_e32 v7, v2, v3
	v_cvt_pk_bf16_f32 v2, v8, v9
	v_cvt_pk_bf16_f32 v3, v10, v11
	v_cvt_pk_bf16_f32 v4, v12, v6
	v_cvt_pk_bf16_f32 v5, v7, v5
	global_store_dwordx4 v[20:21], v[2:5], off
	s_cbranch_vccnz .LBB0_1485
	s_andn2_b64 vcc, exec, s[20:21]
	s_cbranch_vccnz .LBB0_1484
	s_barrier
	s_branch .LBB0_1484
